# v79 + VALU-free load segments in the three GEMM K-loops: B-fragment ds_read bases via one loop-invariant VGPR and immediate offsets (4 v_add_u32 per iteration removed), last VGPR-address LDS-DMA conve
# speedup vs baseline: 1.0069x; 1.0069x over previous
; #define PG8_STAGE(bufoff, gbase, voff) do { _Pragma("unroll") for (int _i = 0; _i < 2; ++_i) \
;         __builtin_amdgcn_global_load_lds((const unsigned*)((const char*)(gbase) + (voff)[_i]), (PG8_LAS unsigned*)(lds + (bufoff) + ldsw + _i * 8192), 16, 0, 0); } while (0)
; #define PG8_LDA(dst, b, h) do { _Pragma("unroll") for (int m = 0; m < 4; ++m) _Pragma("unroll") for (int k = 0; k < 2; ++k) dst[m][k] = *(const PG8_LAS bf16x8*)(lds + PG8_SA(b, h) + aoff + m * 2048 + k * 1024); } while (0)
; #define PG8_LDB(dst, b, h) do { _Pragma("unroll") for (int n = 0; n < 2; ++n) _Pragma("unroll") for (int k = 0; k < 2; ++k) dst[n][k] = *(const PG8_LAS bf16x8*)(lds + PG8_SB(b, h) + boff + n * 2048 + k * 1024); } while (0)
; #define PG8_WAIT_V(n) asm volatile("s_waitcnt vmcnt(" #n ")" ::: "memory")
; template <class Epi, class Sched, bool ALIGN_EPI = false, bool SP2 = false>
; __device__ __forceinline__ void gemm_phase(PG8_LAS unsigned char* lds, const Gemm g, const Sched& S, const Epi& E) {
;     ...
;         const bool has_next = S.next(ui + 1, nxt);
;         const char* nA = has_next ? (const char*)g.A + (size_t)nxt.pm * tstep : cA; const char* nB = has_next ? (const char*)g.Bt + (size_t)nxt.pn * tstep : cB;
;         for (int t = 0; t < nt; t += 2) {
;             const bool last = (t == nt - 2);
;             const char* a1 = cA + (size_t)(t + 1) * kstep;
;             const char* a2 = last ? nA : cA + (size_t)(t + 2) * kstep; const char* b2 = last ? nB : cB + (size_t)(t + 2) * kstep;
;             const char* a3 = a2 + kstep; const char* b3 = b2 + kstep;
;             if (last && has_next) S.a_ready(nxt);
;             if constexpr (SP2) {
;             PG8_LDB(B0, 0, 0); PG8_LDB(B1, 0, 1); PG8_SCHED; PG8_LDA(At, 0, 0); PG8_STAGE(PG8_SA(1, 1), a1 + hstep, voffA);
;             PG8_WAIT_V(8); PG8_WAIT_L(0); PG8_BAR; PG8_MMA(0, 0, At, B0); PG8_MMA(0, 1, At, B1); PG8_BAR; PG8_SCHED;
;             PG8_LDA(At, 0, 1); PG8_STAGE(PG8_SB(0, 0), b2, voffB); PG8_STAGE(PG8_SB(0, 1), b2 + hstep, voffB); PG8_STAGE(PG8_SA(0, 0), a2, voffA);
;     ...
; #pragma unroll
;         for (int a = 0; a < 2; ++a)
; #pragma unroll
;             for (int b = 0; b < 2; ++b)
; #pragma unroll
;                 for (int m = 0; m < 4; ++m)
; #pragma unroll
;                     for (int n = 0; n < 2; ++n) acc[a][b][m][n] = (f32x4){0.f, 0.f, 0.f, 0.f};
;         cur = nxt; cA = nA; cB = nB; ++ui;
.LBB0_1129:
	s_ashr_i32 s79, s78, 31
	s_lshl_b64 s[22:23], s[78:79], 19
	v_readlane_b32 s5, v255, 15
	s_add_u32 s80, s5, s22
	s_addc_u32 s81, s61, s23
	s_and_b64 s[22:23], s[2:3], exec
	s_cselect_b32 s5, s81, s7
	s_cselect_b32 s9, s80, s6
	s_ashr_i32 s77, s76, 31
	s_lshl_b64 s[22:23], s[76:77], 19
	s_add_u32 s82, s55, s22
	s_addc_u32 s83, s56, s23
	s_and_b64 s[22:23], s[2:3], exec
	s_cselect_b32 s22, s83, s11
	s_cselect_b32 s23, s82, s10
	s_add_u32 s6, s6, 0xc000
	s_addc_u32 s7, s7, 0
	s_add_u32 s30, s10, 0x10000
	v_mov_b32_e32 v0, 0
	s_addc_u32 s37, s11, 0
	s_mov_b32 s40, -2
	v_mov_b32_e32 v1, v0
	v_mov_b32_e32 v2, v0
	v_mov_b32_e32 v3, v0
	v_mov_b32_e32 v4, v0
	v_mov_b32_e32 v5, v0
	v_mov_b32_e32 v6, v0
	v_mov_b32_e32 v7, v0
	v_mov_b32_e32 v28, v0
	v_mov_b32_e32 v29, v0
	v_mov_b32_e32 v30, v0
	v_mov_b32_e32 v31, v0
	v_mov_b32_e32 v36, v0
	v_mov_b32_e32 v37, v0
	v_mov_b32_e32 v38, v0
	v_mov_b32_e32 v39, v0
	v_mov_b32_e32 v64, v0
	v_mov_b32_e32 v65, v0
	v_mov_b32_e32 v66, v0
	v_mov_b32_e32 v67, v0
	v_mov_b32_e32 v68, v0
	v_mov_b32_e32 v69, v0
	v_mov_b32_e32 v70, v0
	v_mov_b32_e32 v71, v0
	v_mov_b32_e32 v80, v0
	v_mov_b32_e32 v81, v0
	v_mov_b32_e32 v82, v0
	v_mov_b32_e32 v83, v0
	v_mov_b32_e32 v84, v0
	v_mov_b32_e32 v85, v0
	v_mov_b32_e32 v86, v0
	v_mov_b32_e32 v87, v0
	v_mov_b32_e32 v8, v0
	v_mov_b32_e32 v9, v0
	v_mov_b32_e32 v10, v0
	v_mov_b32_e32 v11, v0
	v_mov_b32_e32 v12, v0
	v_mov_b32_e32 v13, v0
	v_mov_b32_e32 v14, v0
	v_mov_b32_e32 v15, v0
	v_mov_b32_e32 v40, v0
	v_mov_b32_e32 v41, v0
	v_mov_b32_e32 v42, v0
	v_mov_b32_e32 v43, v0
	v_mov_b32_e32 v44, v0
	v_mov_b32_e32 v45, v0
	v_mov_b32_e32 v46, v0
	v_mov_b32_e32 v47, v0
	v_mov_b32_e32 v72, v0
	v_mov_b32_e32 v73, v0
	v_mov_b32_e32 v74, v0
	v_mov_b32_e32 v75, v0
	v_mov_b32_e32 v76, v0
	v_mov_b32_e32 v77, v0
	v_mov_b32_e32 v78, v0
	v_mov_b32_e32 v79, v0
	v_mov_b32_e32 v88, v0
	v_mov_b32_e32 v89, v0
	v_mov_b32_e32 v90, v0
	v_mov_b32_e32 v91, v0
	v_mov_b32_e32 v92, v0
	v_mov_b32_e32 v93, v0
	v_mov_b32_e32 v94, v0
	v_mov_b32_e32 v95, v0
	v_mov_b32_e32 v96, v0
	v_mov_b32_e32 v97, v0
	v_mov_b32_e32 v98, v0
	v_mov_b32_e32 v99, v0
	v_mov_b32_e32 v100, v0
	v_mov_b32_e32 v101, v0
	v_mov_b32_e32 v102, v0
	v_mov_b32_e32 v103, v0
	v_mov_b32_e32 v112, v0
	v_mov_b32_e32 v113, v0
	v_mov_b32_e32 v114, v0
	v_mov_b32_e32 v115, v0
	v_mov_b32_e32 v116, v0
	v_mov_b32_e32 v117, v0
	v_mov_b32_e32 v118, v0
	v_mov_b32_e32 v119, v0
	v_mov_b32_e32 v128, v0
	v_mov_b32_e32 v129, v0
	v_mov_b32_e32 v130, v0
	v_mov_b32_e32 v131, v0
	v_mov_b32_e32 v132, v0
	v_mov_b32_e32 v133, v0
	v_mov_b32_e32 v134, v0
	v_mov_b32_e32 v135, v0
	v_mov_b32_e32 v144, v0
	v_mov_b32_e32 v145, v0
	v_mov_b32_e32 v146, v0
	v_mov_b32_e32 v147, v0
	v_mov_b32_e32 v148, v0
	v_mov_b32_e32 v149, v0
	v_mov_b32_e32 v150, v0
	v_mov_b32_e32 v151, v0
	v_mov_b32_e32 v104, v0
	v_mov_b32_e32 v105, v0
	v_mov_b32_e32 v106, v0
	v_mov_b32_e32 v107, v0
	v_mov_b32_e32 v108, v0
	v_mov_b32_e32 v109, v0
	v_mov_b32_e32 v110, v0
	v_mov_b32_e32 v111, v0
	v_mov_b32_e32 v120, v0
	v_mov_b32_e32 v121, v0
	v_mov_b32_e32 v122, v0
	v_mov_b32_e32 v123, v0
	v_mov_b32_e32 v124, v0
	v_mov_b32_e32 v125, v0
	v_mov_b32_e32 v126, v0
	v_mov_b32_e32 v127, v0
	v_mov_b32_e32 v136, v0
	v_mov_b32_e32 v137, v0
	v_mov_b32_e32 v138, v0
	v_mov_b32_e32 v139, v0
	v_mov_b32_e32 v140, v0
	v_mov_b32_e32 v141, v0
	v_mov_b32_e32 v142, v0
	v_mov_b32_e32 v143, v0
	v_mov_b32_e32 v152, v0
	v_mov_b32_e32 v153, v0
	v_mov_b32_e32 v154, v0
	v_mov_b32_e32 v155, v0
	v_mov_b32_e32 v156, v0
	v_mov_b32_e32 v157, v0
	v_mov_b32_e32 v158, v0
	v_mov_b32_e32 v159, v0
	v_add_u32_e32 v246, 0x10000, v192
.LBB0_1130:
	s_add_u32 s10, s6, 0x4000
	s_addc_u32 s11, s7, 0
	s_cmp_eq_u32 s40, 12
	s_cselect_b32 s86, s9, s10
	s_cselect_b32 s87, s5, s11
	s_cselect_b32 s84, s23, s30
	s_cselect_b32 s85, s22, s37
	s_add_u32 s10, s86, 0x8000
	s_addc_u32 s11, s87, 0
	s_add_i32 s77, 0, 0x10000
	s_add_i32 s79, 0, 0x14000
	ds_read_b128 v[16:19], v246
	ds_read_b128 v[20:23], v246 offset:1024
	ds_read_b128 v[24:27], v246 offset:2048
	ds_read_b128 v[32:35], v246 offset:3072
	ds_read_b128 v[48:51], v246 offset:16384
	ds_read_b128 v[52:55], v246 offset:17408
	ds_read_b128 v[56:59], v246 offset:18432
	ds_read_b128 v[60:63], v246 offset:19456
	s_add_i32 m0, s33, 0xc000
	ds_read_b128 v[160:163], v193
	ds_read_b128 v[164:167], v193 offset:1024
	ds_read_b128 v[180:183], v193 offset:2048
	ds_read_b128 v[184:187], v193 offset:3072
	ds_read_b128 v[188:191], v193 offset:4096
	ds_read_b128 v[194:197], v193 offset:5120
	ds_read_b128 v[198:201], v193 offset:6144
	ds_read_b128 v[202:205], v193 offset:7168
	global_load_lds_dwordx4 v176, s[6:7]
	s_add_i32 m0, s33, 0xe000
	s_nop 0
	global_load_lds_dwordx4 v178, s[6:7]
	s_waitcnt vmcnt(8) lgkmcnt(0)
	s_barrier
; #define PG8_STAGE(bufoff, gbase, voff) do { _Pragma("unroll") for (int _i = 0; _i < 2; ++_i) \
;         __builtin_amdgcn_global_load_lds((const unsigned*)((const char*)(gbase) + (voff)[_i]), (PG8_LAS unsigned*)(lds + (bufoff) + ldsw + _i * 8192), 16, 0, 0); } while (0)
; #define PG8_LDA(dst, b, h) do { _Pragma("unroll") for (int m = 0; m < 4; ++m) _Pragma("unroll") for (int k = 0; k < 2; ++k) dst[m][k] = *(const PG8_LAS bf16x8*)(lds + PG8_SA(b, h) + aoff + m * 2048 + k * 1024); } while (0)
; #define PG8_MMA(ai, bj, At, Bt) do { __builtin_amdgcn_s_setprio(1); _Pragma("unroll") for (int m = 0; m < 4; ++m) _Pragma("unroll") for (int n = 0; n < 2; ++n) _Pragma("unroll") for (int k = 0; k < 2; ++k) \
;         acc[ai][bj][m][n] = __builtin_amdgcn_mfma_f32_16x16x32_bf16(Bt[n][k], At[m][k], acc[ai][bj][m][n], 0, 0, 0); __builtin_amdgcn_s_setprio(0); } while (0)
; #define PG8_WAIT_V(n) asm volatile("s_waitcnt vmcnt(" #n ")" ::: "memory")
; #define PG8_WAIT_L(n) asm volatile("s_waitcnt lgkmcnt(" #n ")" ::: "memory")
; #define PG8_BAR __builtin_amdgcn_s_barrier()
; #define PG8_SCHED __builtin_amdgcn_sched_barrier(0)
; template <class Epi, class Sched, bool ALIGN_EPI = false, bool SP2 = false>
; __device__ __forceinline__ void gemm_phase(PG8_LAS unsigned char* lds, const Gemm g, const Sched& S, const Epi& E) {
;     ...
;             PG8_WAIT_V(8); PG8_WAIT_L(0); PG8_BAR; PG8_MMA(0, 0, At, B0); PG8_MMA(0, 1, At, B1); PG8_BAR; PG8_SCHED;
;             PG8_LDA(At, 0, 1); PG8_STAGE(PG8_SB(0, 0), b2, voffB); PG8_STAGE(PG8_SB(0, 1), b2 + hstep, voffB); PG8_STAGE(PG8_SA(0, 0), a2, voffA);
;             PG8_WAIT_V(8); PG8_WAIT_L(0); PG8_BAR; PG8_MMA(1, 0, At, B0); PG8_MMA(1, 1, At, B1); PG8_BAR; PG8_SCHED;
	v_mfma_f32_16x16x32_bf16 v[156:159], v[16:19], v[160:163], v[156:159]
	v_mfma_f32_16x16x32_bf16 v[152:155], v[24:27], v[160:163], v[152:155]
	v_mfma_f32_16x16x32_bf16 v[140:143], v[16:19], v[180:183], v[140:143]
	v_mfma_f32_16x16x32_bf16 v[136:139], v[24:27], v[180:183], v[136:139]
	v_mfma_f32_16x16x32_bf16 v[124:127], v[16:19], v[188:191], v[124:127]
	v_mfma_f32_16x16x32_bf16 v[120:123], v[24:27], v[188:191], v[120:123]
	v_mfma_f32_16x16x32_bf16 v[108:111], v[16:19], v[198:201], v[108:111]
	v_mfma_f32_16x16x32_bf16 v[104:107], v[24:27], v[198:201], v[104:107]
	v_mfma_f32_16x16x32_bf16 v[156:159], v[20:23], v[164:167], v[156:159]
	v_mfma_f32_16x16x32_bf16 v[152:155], v[32:35], v[164:167], v[152:155]
	v_mfma_f32_16x16x32_bf16 v[140:143], v[20:23], v[184:187], v[140:143]
	v_mfma_f32_16x16x32_bf16 v[136:139], v[32:35], v[184:187], v[136:139]
	v_mfma_f32_16x16x32_bf16 v[124:127], v[20:23], v[194:197], v[124:127]
	v_mfma_f32_16x16x32_bf16 v[120:123], v[32:35], v[194:197], v[120:123]
	v_mfma_f32_16x16x32_bf16 v[108:111], v[20:23], v[202:205], v[108:111]
	v_mfma_f32_16x16x32_bf16 v[104:107], v[32:35], v[202:205], v[104:107]
	v_mfma_f32_16x16x32_bf16 v[148:151], v[48:51], v[160:163], v[148:151]
	v_mfma_f32_16x16x32_bf16 v[144:147], v[56:59], v[160:163], v[144:147]
	v_mfma_f32_16x16x32_bf16 v[132:135], v[48:51], v[180:183], v[132:135]
	v_mfma_f32_16x16x32_bf16 v[128:131], v[56:59], v[180:183], v[128:131]
	v_mfma_f32_16x16x32_bf16 v[116:119], v[48:51], v[188:191], v[116:119]
	v_mfma_f32_16x16x32_bf16 v[112:115], v[56:59], v[188:191], v[112:115]
	v_mfma_f32_16x16x32_bf16 v[100:103], v[48:51], v[198:201], v[100:103]
	v_mfma_f32_16x16x32_bf16 v[96:99], v[56:59], v[198:201], v[96:99]
	v_mfma_f32_16x16x32_bf16 v[148:151], v[52:55], v[164:167], v[148:151]
	v_mfma_f32_16x16x32_bf16 v[144:147], v[60:63], v[164:167], v[144:147]
	v_mfma_f32_16x16x32_bf16 v[132:135], v[52:55], v[184:187], v[132:135]
	v_mfma_f32_16x16x32_bf16 v[128:131], v[60:63], v[184:187], v[128:131]
	v_mfma_f32_16x16x32_bf16 v[116:119], v[52:55], v[194:197], v[116:119]
	v_mfma_f32_16x16x32_bf16 v[112:115], v[60:63], v[194:197], v[112:115]
	v_mfma_f32_16x16x32_bf16 v[100:103], v[52:55], v[202:205], v[100:103]
	v_mfma_f32_16x16x32_bf16 v[96:99], v[60:63], v[202:205], v[96:99]
	s_barrier
	s_add_i32 s77, s77, s57
	s_mov_b32 m0, s77
	ds_read_b128 v[160:163], v193 offset:16384
	ds_read_b128 v[164:167], v193 offset:17408
	ds_read_b128 v[180:183], v193 offset:18432
	ds_read_b128 v[184:187], v193 offset:19456
	ds_read_b128 v[188:191], v193 offset:20480
	ds_read_b128 v[194:197], v193 offset:21504
	ds_read_b128 v[198:201], v193 offset:22528
	ds_read_b128 v[202:205], v193 offset:23552
	global_load_lds_dwordx4 v170, s[84:85]
	s_add_i32 m0, s77, 0x2000
	s_add_u32 s88, s84, 0x4000
	s_addc_u32 s89, s85, 0
	s_add_i32 s77, s79, s57
	global_load_lds_dwordx4 v174, s[84:85]
	s_mov_b32 m0, s77
	s_nop 0
	global_load_lds_dwordx4 v170, s[88:89]
	s_add_i32 m0, s77, 0x2000
	s_nop 0
	global_load_lds_dwordx4 v174, s[88:89]
	s_mov_b32 m0, s33
	s_nop 0
	global_load_lds_dwordx4 v168, s[86:87]
	s_mov_b32 m0, s42
	s_nop 0
	global_load_lds_dwordx4 v172, s[86:87]
	s_waitcnt vmcnt(8) lgkmcnt(0)
	s_barrier
	v_mfma_f32_16x16x32_bf16 v[92:95], v[16:19], v[160:163], v[92:95]
	v_mfma_f32_16x16x32_bf16 v[88:91], v[24:27], v[160:163], v[88:91]
	v_mfma_f32_16x16x32_bf16 v[76:79], v[16:19], v[180:183], v[76:79]
	v_mfma_f32_16x16x32_bf16 v[72:75], v[24:27], v[180:183], v[72:75]
	v_mfma_f32_16x16x32_bf16 v[44:47], v[16:19], v[188:191], v[44:47]
	v_mfma_f32_16x16x32_bf16 v[40:43], v[24:27], v[188:191], v[40:43]
	v_mfma_f32_16x16x32_bf16 v[12:15], v[16:19], v[198:201], v[12:15]
	v_mfma_f32_16x16x32_bf16 v[8:11], v[24:27], v[198:201], v[8:11]
	v_mfma_f32_16x16x32_bf16 v[92:95], v[20:23], v[164:167], v[92:95]
	v_mfma_f32_16x16x32_bf16 v[88:91], v[32:35], v[164:167], v[88:91]
	v_mfma_f32_16x16x32_bf16 v[76:79], v[20:23], v[184:187], v[76:79]
	v_mfma_f32_16x16x32_bf16 v[72:75], v[32:35], v[184:187], v[72:75]
	v_mfma_f32_16x16x32_bf16 v[44:47], v[20:23], v[194:197], v[44:47]
	v_mfma_f32_16x16x32_bf16 v[40:43], v[32:35], v[194:197], v[40:43]
	v_mfma_f32_16x16x32_bf16 v[12:15], v[20:23], v[202:205], v[12:15]
	v_mfma_f32_16x16x32_bf16 v[8:11], v[32:35], v[202:205], v[8:11]
	v_mfma_f32_16x16x32_bf16 v[36:39], v[48:51], v[188:191], v[36:39]
	v_mfma_f32_16x16x32_bf16 v[28:31], v[56:59], v[188:191], v[28:31]
	v_mfma_f32_16x16x32_bf16 v[4:7], v[48:51], v[198:201], v[4:7]
	v_mfma_f32_16x16x32_bf16 v[0:3], v[56:59], v[198:201], v[0:3]
	v_mfma_f32_16x16x32_bf16 v[16:19], v[48:51], v[160:163], v[84:87]
	v_mfma_f32_16x16x32_bf16 v[20:23], v[56:59], v[160:163], v[80:83]
	v_mfma_f32_16x16x32_bf16 v[24:27], v[48:51], v[180:183], v[68:71]
	v_mfma_f32_16x16x32_bf16 v[32:35], v[56:59], v[180:183], v[64:67]
	v_mfma_f32_16x16x32_bf16 v[36:39], v[52:55], v[194:197], v[36:39]
	v_mfma_f32_16x16x32_bf16 v[28:31], v[60:63], v[194:197], v[28:31]
	v_mfma_f32_16x16x32_bf16 v[4:7], v[52:55], v[202:205], v[4:7]
	v_mfma_f32_16x16x32_bf16 v[0:3], v[60:63], v[202:205], v[0:3]
	v_mfma_f32_16x16x32_bf16 v[16:19], v[52:55], v[164:167], v[16:19]
	v_mfma_f32_16x16x32_bf16 v[20:23], v[60:63], v[164:167], v[20:23]
	v_mfma_f32_16x16x32_bf16 v[24:27], v[52:55], v[184:187], v[24:27]
	v_mfma_f32_16x16x32_bf16 v[32:35], v[60:63], v[184:187], v[32:35]
	s_barrier
; #define PG8_STAGE(bufoff, gbase, voff) do { _Pragma("unroll") for (int _i = 0; _i < 2; ++_i) \
;         __builtin_amdgcn_global_load_lds((const unsigned*)((const char*)(gbase) + (voff)[_i]), (PG8_LAS unsigned*)(lds + (bufoff) + ldsw + _i * 8192), 16, 0, 0); } while (0)
; #define PG8_LDA(dst, b, h) do { _Pragma("unroll") for (int m = 0; m < 4; ++m) _Pragma("unroll") for (int k = 0; k < 2; ++k) dst[m][k] = *(const PG8_LAS bf16x8*)(lds + PG8_SA(b, h) + aoff + m * 2048 + k * 1024); } while (0)
; #define PG8_LDB(dst, b, h) do { _Pragma("unroll") for (int n = 0; n < 2; ++n) _Pragma("unroll") for (int k = 0; k < 2; ++k) dst[n][k] = *(const PG8_LAS bf16x8*)(lds + PG8_SB(b, h) + boff + n * 2048 + k * 1024); } while (0)
; #define PG8_MMA(ai, bj, At, Bt) do { __builtin_amdgcn_s_setprio(1); _Pragma("unroll") for (int m = 0; m < 4; ++m) _Pragma("unroll") for (int n = 0; n < 2; ++n) _Pragma("unroll") for (int k = 0; k < 2; ++k) \
;         acc[ai][bj][m][n] = __builtin_amdgcn_mfma_f32_16x16x32_bf16(Bt[n][k], At[m][k], acc[ai][bj][m][n], 0, 0, 0); __builtin_amdgcn_s_setprio(0); } while (0)
; #define PG8_WAIT_V(n) asm volatile("s_waitcnt vmcnt(" #n ")" ::: "memory")
; #define PG8_WAIT_L(n) asm volatile("s_waitcnt lgkmcnt(" #n ")" ::: "memory")
; #define PG8_BAR __builtin_amdgcn_s_barrier()
; #define PG8_SCHED __builtin_amdgcn_sched_barrier(0)
; template <class Epi, class Sched, bool ALIGN_EPI = false, bool SP2 = false>
; __device__ __forceinline__ void gemm_phase(PG8_LAS unsigned char* lds, const Gemm g, const Sched& S, const Epi& E) {
;     ...
;             PG8_LDB(B0, 1, 0); PG8_LDB(B1, 1, 1); PG8_SCHED; PG8_LDA(At, 1, 0); PG8_STAGE(PG8_SA(0, 1), a2 + hstep, voffA);
;             PG8_WAIT_V(8); PG8_WAIT_L(0); PG8_BAR; PG8_MMA(0, 0, At, B0); PG8_MMA(0, 1, At, B1); PG8_BAR; PG8_SCHED;
;             PG8_LDA(At, 1, 1); PG8_STAGE(PG8_SB(1, 0), b3, voffB); PG8_STAGE(PG8_SB(1, 1), b3 + hstep, voffB); PG8_STAGE(PG8_SA(1, 0), a3, voffA);
;             PG8_WAIT_V(8); PG8_WAIT_L(0); PG8_BAR; PG8_MMA(1, 0, At, B0); PG8_MMA(1, 1, At, B1); PG8_BAR; PG8_SCHED;
	s_add_i32 s77, 0, 0x18000
	s_add_i32 s79, 0, 0x1c000
	ds_read_b128 v[48:51], v246 offset:32768
	ds_read_b128 v[52:55], v246 offset:33792
	ds_read_b128 v[56:59], v246 offset:34816
	ds_read_b128 v[60:63], v246 offset:35840
	ds_read_b128 v[160:163], v246 offset:49152
	ds_read_b128 v[164:167], v246 offset:50176
	ds_read_b128 v[180:183], v246 offset:51200
	ds_read_b128 v[184:187], v246 offset:52224
	s_add_u32 s86, s86, 0x4000
	s_addc_u32 s87, s87, 0
	s_mov_b32 m0, s64
	ds_read_b128 v[64:67], v193 offset:32768
	ds_read_b128 v[68:71], v193 offset:33792
	ds_read_b128 v[80:83], v193 offset:34816
	ds_read_b128 v[84:87], v193 offset:35840
	ds_read_b128 v[188:191], v193 offset:36864
	ds_read_b128 v[194:197], v193 offset:37888
	ds_read_b128 v[198:201], v193 offset:38912
	ds_read_b128 v[202:205], v193 offset:39936
	global_load_lds_dwordx4 v168, s[86:87]
	s_mov_b32 m0, s65
	s_nop 0
	global_load_lds_dwordx4 v172, s[86:87]
	s_waitcnt vmcnt(8) lgkmcnt(0)
	s_barrier
	v_mfma_f32_16x16x32_bf16 v[156:159], v[48:51], v[64:67], v[156:159]
	v_mfma_f32_16x16x32_bf16 v[152:155], v[56:59], v[64:67], v[152:155]
	v_mfma_f32_16x16x32_bf16 v[140:143], v[48:51], v[80:83], v[140:143]
	v_mfma_f32_16x16x32_bf16 v[136:139], v[56:59], v[80:83], v[136:139]
	v_mfma_f32_16x16x32_bf16 v[124:127], v[48:51], v[188:191], v[124:127]
	v_mfma_f32_16x16x32_bf16 v[120:123], v[56:59], v[188:191], v[120:123]
	v_mfma_f32_16x16x32_bf16 v[108:111], v[48:51], v[198:201], v[108:111]
	v_mfma_f32_16x16x32_bf16 v[104:107], v[56:59], v[198:201], v[104:107]
	v_mfma_f32_16x16x32_bf16 v[156:159], v[52:55], v[68:71], v[156:159]
	v_mfma_f32_16x16x32_bf16 v[152:155], v[60:63], v[68:71], v[152:155]
	v_mfma_f32_16x16x32_bf16 v[140:143], v[52:55], v[84:87], v[140:143]
	v_mfma_f32_16x16x32_bf16 v[136:139], v[60:63], v[84:87], v[136:139]
	v_mfma_f32_16x16x32_bf16 v[124:127], v[52:55], v[194:197], v[124:127]
	v_mfma_f32_16x16x32_bf16 v[120:123], v[60:63], v[194:197], v[120:123]
	v_mfma_f32_16x16x32_bf16 v[108:111], v[52:55], v[202:205], v[108:111]
	v_mfma_f32_16x16x32_bf16 v[104:107], v[60:63], v[202:205], v[104:107]
	v_mfma_f32_16x16x32_bf16 v[148:151], v[160:163], v[64:67], v[148:151]
	v_mfma_f32_16x16x32_bf16 v[64:67], v[180:183], v[64:67], v[144:147]
	v_mfma_f32_16x16x32_bf16 v[144:147], v[184:187], v[68:71], v[64:67]
	v_mfma_f32_16x16x32_bf16 v[64:67], v[160:163], v[80:83], v[132:135]
	v_mfma_f32_16x16x32_bf16 v[132:135], v[164:167], v[84:87], v[64:67]
	v_mfma_f32_16x16x32_bf16 v[64:67], v[180:183], v[80:83], v[128:131]
	v_mfma_f32_16x16x32_bf16 v[128:131], v[184:187], v[84:87], v[64:67]
	v_mfma_f32_16x16x32_bf16 v[64:67], v[160:163], v[188:191], v[116:119]
	v_mfma_f32_16x16x32_bf16 v[116:119], v[164:167], v[194:197], v[64:67]
	v_mfma_f32_16x16x32_bf16 v[64:67], v[180:183], v[188:191], v[112:115]
	v_mfma_f32_16x16x32_bf16 v[112:115], v[184:187], v[194:197], v[64:67]
	v_mfma_f32_16x16x32_bf16 v[64:67], v[160:163], v[198:201], v[100:103]
	v_mfma_f32_16x16x32_bf16 v[100:103], v[164:167], v[202:205], v[64:67]
	v_mfma_f32_16x16x32_bf16 v[64:67], v[180:183], v[198:201], v[96:99]
	v_mfma_f32_16x16x32_bf16 v[148:151], v[164:167], v[68:71], v[148:151]
	v_mfma_f32_16x16x32_bf16 v[96:99], v[184:187], v[202:205], v[64:67]
	s_barrier
	s_add_u32 s86, s84, 0x8000
	s_addc_u32 s87, s85, 0
	s_add_i32 s77, s77, s57
	s_mov_b32 m0, s77
	ds_read_b128 v[64:67], v193 offset:49152
	ds_read_b128 v[68:71], v193 offset:50176
	ds_read_b128 v[188:191], v193 offset:51200
	ds_read_b128 v[194:197], v193 offset:52224
	ds_read_b128 v[198:201], v193 offset:53248
	ds_read_b128 v[202:205], v193 offset:54272
	ds_read_b128 v[206:209], v193 offset:55296
	ds_read_b128 v[210:213], v193 offset:56320
	global_load_lds_dwordx4 v170, s[86:87]
	s_add_i32 m0, s77, 0x2000
	s_add_u32 s84, s84, 0xc000
	s_addc_u32 s85, s85, 0
	s_add_i32 s77, s79, s57
	global_load_lds_dwordx4 v174, s[86:87]
	s_mov_b32 m0, s77
	s_nop 0
	global_load_lds_dwordx4 v170, s[84:85]
	s_add_i32 m0, s77, 0x2000
	s_nop 0
	global_load_lds_dwordx4 v174, s[84:85]
	s_mov_b32 m0, s53
	s_nop 0
	global_load_lds_dwordx4 v168, s[10:11]
	s_mov_b32 m0, s27
	s_nop 0
	global_load_lds_dwordx4 v172, s[10:11]
	s_waitcnt vmcnt(8) lgkmcnt(0)
	s_barrier
	v_mfma_f32_16x16x32_bf16 v[80:83], v[48:51], v[64:67], v[92:95]
	v_mfma_f32_16x16x32_bf16 v[92:95], v[52:55], v[68:71], v[80:83]
	v_mfma_f32_16x16x32_bf16 v[80:83], v[56:59], v[64:67], v[88:91]
	v_mfma_f32_16x16x32_bf16 v[76:79], v[48:51], v[188:191], v[76:79]
	v_mfma_f32_16x16x32_bf16 v[72:75], v[56:59], v[188:191], v[72:75]
	v_mfma_f32_16x16x32_bf16 v[44:47], v[48:51], v[198:201], v[44:47]
	v_mfma_f32_16x16x32_bf16 v[40:43], v[56:59], v[198:201], v[40:43]
	v_mfma_f32_16x16x32_bf16 v[12:15], v[48:51], v[206:209], v[12:15]
	v_mfma_f32_16x16x32_bf16 v[8:11], v[56:59], v[206:209], v[8:11]
	v_mfma_f32_16x16x32_bf16 v[88:91], v[60:63], v[68:71], v[80:83]
	v_mfma_f32_16x16x32_bf16 v[76:79], v[52:55], v[194:197], v[76:79]
	v_mfma_f32_16x16x32_bf16 v[72:75], v[60:63], v[194:197], v[72:75]
	v_mfma_f32_16x16x32_bf16 v[44:47], v[52:55], v[202:205], v[44:47]
	v_mfma_f32_16x16x32_bf16 v[40:43], v[60:63], v[202:205], v[40:43]
	v_mfma_f32_16x16x32_bf16 v[12:15], v[52:55], v[210:213], v[12:15]
	v_mfma_f32_16x16x32_bf16 v[8:11], v[60:63], v[210:213], v[8:11]
	v_mfma_f32_16x16x32_bf16 v[16:19], v[160:163], v[64:67], v[16:19]
	v_mfma_f32_16x16x32_bf16 v[84:87], v[164:167], v[68:71], v[16:19]
	v_mfma_f32_16x16x32_bf16 v[16:19], v[180:183], v[64:67], v[20:23]
	v_mfma_f32_16x16x32_bf16 v[80:83], v[184:187], v[68:71], v[16:19]
	v_mfma_f32_16x16x32_bf16 v[16:19], v[160:163], v[188:191], v[24:27]
	v_mfma_f32_16x16x32_bf16 v[68:71], v[164:167], v[194:197], v[16:19]
	v_mfma_f32_16x16x32_bf16 v[16:19], v[180:183], v[188:191], v[32:35]
	v_mfma_f32_16x16x32_bf16 v[64:67], v[184:187], v[194:197], v[16:19]
	v_mfma_f32_16x16x32_bf16 v[16:19], v[160:163], v[198:201], v[36:39]
	v_mfma_f32_16x16x32_bf16 v[36:39], v[164:167], v[202:205], v[16:19]
	v_mfma_f32_16x16x32_bf16 v[16:19], v[180:183], v[198:201], v[28:31]
	v_mfma_f32_16x16x32_bf16 v[4:7], v[160:163], v[206:209], v[4:7]
	v_mfma_f32_16x16x32_bf16 v[0:3], v[180:183], v[206:209], v[0:3]
	v_mfma_f32_16x16x32_bf16 v[28:31], v[184:187], v[202:205], v[16:19]
	v_mfma_f32_16x16x32_bf16 v[4:7], v[164:167], v[210:213], v[4:7]
	v_mfma_f32_16x16x32_bf16 v[0:3], v[184:187], v[210:213], v[0:3]
	s_barrier
	s_add_i32 s40, s40, 2
	s_add_u32 s6, s6, 0x10000
	s_addc_u32 s7, s7, 0
	s_add_u32 s30, s30, 0x10000
	s_addc_u32 s37, s37, 0
	s_cmp_gt_u32 s40, 13
	s_cbranch_scc0 .LBB0_1130
	s_and_b64 vcc, exec, s[70:71]
	s_cbranch_vccz .LBB0_1133
	s_barrier

; #define PG8_STAGE(bufoff, gbase, voff) do { _Pragma("unroll") for (int _i = 0; _i < 2; ++_i) \
;         __builtin_amdgcn_global_load_lds((const unsigned*)((const char*)(gbase) + (voff)[_i]), (PG8_LAS unsigned*)(lds + (bufoff) + ldsw + _i * 8192), 16, 0, 0); } while (0)
; #define PG8_LDA(dst, b, h) do { _Pragma("unroll") for (int m = 0; m < 4; ++m) _Pragma("unroll") for (int k = 0; k < 2; ++k) dst[m][k] = *(const PG8_LAS bf16x8*)(lds + PG8_SA(b, h) + aoff + m * 2048 + k * 1024); } while (0)
; #define PG8_LDB(dst, b, h) do { _Pragma("unroll") for (int n = 0; n < 2; ++n) _Pragma("unroll") for (int k = 0; k < 2; ++k) dst[n][k] = *(const PG8_LAS bf16x8*)(lds + PG8_SB(b, h) + boff + n * 2048 + k * 1024); } while (0)
; #define PG8_WAIT_V(n) asm volatile("s_waitcnt vmcnt(" #n ")" ::: "memory")
; #define PG8_WAIT_L(n) asm volatile("s_waitcnt lgkmcnt(" #n ")" ::: "memory")
; #define PG8_BAR __builtin_amdgcn_s_barrier()
; #define PG8_SCHED __builtin_amdgcn_sched_barrier(0)
; template <class Epi, class Sched, bool ALIGN_EPI = false, bool SP2 = false>
; __device__ __forceinline__ void gemm_phase(PG8_LAS unsigned char* lds, const Gemm g, const Sched& S, const Epi& E) {
;     ...
;         for (int t = 0; t < nt; t += 2) {
;             const bool last = (t == nt - 2);
;             const char* a1 = cA + (size_t)(t + 1) * kstep;
;             const char* a2 = last ? nA : cA + (size_t)(t + 2) * kstep; const char* b2 = last ? nB : cB + (size_t)(t + 2) * kstep;
;             const char* a3 = a2 + kstep; const char* b3 = b2 + kstep;
;             if (last && has_next) S.a_ready(nxt);
;             if constexpr (SP2) {
;             PG8_LDB(B0, 0, 0); PG8_LDB(B1, 0, 1); PG8_SCHED; PG8_LDA(At, 0, 0); PG8_STAGE(PG8_SA(1, 1), a1 + hstep, voffA);
;             PG8_WAIT_V(8); PG8_WAIT_L(0); PG8_BAR; PG8_MMA(0, 0, At, B0); PG8_MMA(0, 1, At, B1); PG8_BAR; PG8_SCHED;
;             PG8_LDA(At, 0, 1); PG8_STAGE(PG8_SB(0, 0), b2, voffB); PG8_STAGE(PG8_SB(0, 1), b2 + hstep, voffB); PG8_STAGE(PG8_SA(0, 0), a2, voffA);
;     ...
; #pragma unroll
;         for (int a = 0; a < 2; ++a)
; #pragma unroll
;             for (int b = 0; b < 2; ++b)
; #pragma unroll
;                 for (int m = 0; m < 4; ++m)
; #pragma unroll
;                     for (int n = 0; n < 2; ++n) acc[a][b][m][n] = (f32x4){0.f, 0.f, 0.f, 0.f};
;         cur = nxt; cA = nA; cB = nB; ++ui;
.LBB0_1321:
	s_add_u32 s16, s16, 0xc000
	s_addc_u32 s17, s17, 0
	s_add_u32 s66, s18, 0x10000
	v_mov_b32_e32 v0, 0
	s_addc_u32 s67, s19, 0
	s_mov_b32 s18, 0
	v_mov_b32_e32 v1, v0
	v_mov_b32_e32 v2, v0
	v_mov_b32_e32 v3, v0
	v_mov_b32_e32 v4, v0
	v_mov_b32_e32 v5, v0
	v_mov_b32_e32 v6, v0
	v_mov_b32_e32 v7, v0
	v_mov_b32_e32 v16, v0
	v_mov_b32_e32 v17, v0
	v_mov_b32_e32 v18, v0
	v_mov_b32_e32 v19, v0
	v_mov_b32_e32 v20, v0
	v_mov_b32_e32 v21, v0
	v_mov_b32_e32 v22, v0
	v_mov_b32_e32 v23, v0
	v_mov_b32_e32 v32, v0
	v_mov_b32_e32 v33, v0
	v_mov_b32_e32 v34, v0
	v_mov_b32_e32 v35, v0
	v_mov_b32_e32 v36, v0
	v_mov_b32_e32 v37, v0
	v_mov_b32_e32 v38, v0
	v_mov_b32_e32 v39, v0
	v_mov_b32_e32 v48, v0
	v_mov_b32_e32 v49, v0
	v_mov_b32_e32 v50, v0
	v_mov_b32_e32 v51, v0
	v_mov_b32_e32 v52, v0
	v_mov_b32_e32 v53, v0
	v_mov_b32_e32 v54, v0
	v_mov_b32_e32 v55, v0
	v_mov_b32_e32 v8, v0
	v_mov_b32_e32 v9, v0
	v_mov_b32_e32 v10, v0
	v_mov_b32_e32 v11, v0
	v_mov_b32_e32 v12, v0
	v_mov_b32_e32 v13, v0
	v_mov_b32_e32 v14, v0
	v_mov_b32_e32 v15, v0
	v_mov_b32_e32 v24, v0
	v_mov_b32_e32 v25, v0
	v_mov_b32_e32 v26, v0
	v_mov_b32_e32 v27, v0
	v_mov_b32_e32 v28, v0
	v_mov_b32_e32 v29, v0
	v_mov_b32_e32 v30, v0
	v_mov_b32_e32 v31, v0
	v_mov_b32_e32 v40, v0
	v_mov_b32_e32 v41, v0
	v_mov_b32_e32 v42, v0
	v_mov_b32_e32 v43, v0
	v_mov_b32_e32 v44, v0
	v_mov_b32_e32 v45, v0
	v_mov_b32_e32 v46, v0
	v_mov_b32_e32 v47, v0
	v_mov_b32_e32 v56, v0
	v_mov_b32_e32 v57, v0
	v_mov_b32_e32 v58, v0
	v_mov_b32_e32 v59, v0
	v_mov_b32_e32 v60, v0
	v_mov_b32_e32 v61, v0
	v_mov_b32_e32 v62, v0
	v_mov_b32_e32 v63, v0
	v_mov_b32_e32 v64, v0
	v_mov_b32_e32 v65, v0
	v_mov_b32_e32 v66, v0
	v_mov_b32_e32 v67, v0
	v_mov_b32_e32 v68, v0
	v_mov_b32_e32 v69, v0
	v_mov_b32_e32 v70, v0
	v_mov_b32_e32 v71, v0
	v_mov_b32_e32 v88, v0
	v_mov_b32_e32 v89, v0
	v_mov_b32_e32 v90, v0
	v_mov_b32_e32 v91, v0
	v_mov_b32_e32 v92, v0
	v_mov_b32_e32 v93, v0
	v_mov_b32_e32 v94, v0
	v_mov_b32_e32 v95, v0
	v_mov_b32_e32 v112, v0
	v_mov_b32_e32 v113, v0
	v_mov_b32_e32 v114, v0
	v_mov_b32_e32 v115, v0
	v_mov_b32_e32 v116, v0
	v_mov_b32_e32 v117, v0
	v_mov_b32_e32 v118, v0
	v_mov_b32_e32 v119, v0
	v_mov_b32_e32 v132, v0
	v_mov_b32_e32 v133, v0
	v_mov_b32_e32 v134, v0
	v_mov_b32_e32 v135, v0
	v_mov_b32_e32 v140, v0
	v_mov_b32_e32 v141, v0
	v_mov_b32_e32 v142, v0
	v_mov_b32_e32 v143, v0
	v_mov_b32_e32 v72, v0
	v_mov_b32_e32 v73, v0
	v_mov_b32_e32 v74, v0
	v_mov_b32_e32 v75, v0
	v_mov_b32_e32 v76, v0
	v_mov_b32_e32 v77, v0
	v_mov_b32_e32 v78, v0
	v_mov_b32_e32 v79, v0
	v_mov_b32_e32 v96, v0
	v_mov_b32_e32 v97, v0
	v_mov_b32_e32 v98, v0
	v_mov_b32_e32 v99, v0
	v_mov_b32_e32 v100, v0
	v_mov_b32_e32 v101, v0
	v_mov_b32_e32 v102, v0
	v_mov_b32_e32 v103, v0
	v_mov_b32_e32 v120, v0
	v_mov_b32_e32 v121, v0
	v_mov_b32_e32 v122, v0
	v_mov_b32_e32 v123, v0
	v_mov_b32_e32 v124, v0
	v_mov_b32_e32 v125, v0
	v_mov_b32_e32 v126, v0
	v_mov_b32_e32 v127, v0
	v_mov_b32_e32 v144, v0
	v_mov_b32_e32 v145, v0
	v_mov_b32_e32 v146, v0
	v_mov_b32_e32 v147, v0
	v_mov_b32_e32 v148, v0
	v_mov_b32_e32 v149, v0
	v_mov_b32_e32 v150, v0
	v_mov_b32_e32 v151, v0
	v_add_u32_e32 v246, 0x10000, v206
.LBB0_1322:
	s_add_i32 s75, s18, 2
	s_add_u32 s19, s16, 0x4000
	s_addc_u32 s20, s17, 0
	s_cmp_eq_u32 s59, s18
	s_cselect_b32 s64, s0, s19
	s_cselect_b32 s65, s1, s20
	s_cselect_b32 s20, s14, s66
	s_cselect_b32 s21, s15, s67
	s_add_u32 s18, s64, 0x8000
	s_addc_u32 s19, s65, 0
	s_add_i32 s76, 0, 0x10000
	s_add_i32 s78, 0, 0x14000
	ds_read_b128 v[80:83], v246
	ds_read_b128 v[84:87], v246 offset:1024
	ds_read_b128 v[104:107], v246 offset:2048
	ds_read_b128 v[108:111], v246 offset:3072
	ds_read_b128 v[128:131], v246 offset:16384
	ds_read_b128 v[136:139], v246 offset:17408
	ds_read_b128 v[152:155], v246 offset:18432
	ds_read_b128 v[156:159], v246 offset:19456
	s_add_i32 m0, s41, 0xc000
	ds_read_b128 v[160:163], v207
	ds_read_b128 v[164:167], v207 offset:1024
	ds_read_b128 v[168:171], v207 offset:2048
	ds_read_b128 v[172:175], v207 offset:3072
	ds_read_b128 v[176:179], v207 offset:4096
	ds_read_b128 v[180:183], v207 offset:5120
	ds_read_b128 v[198:201], v207 offset:6144
	ds_read_b128 v[202:205], v207 offset:7168
	global_load_lds_dwordx4 v194, s[16:17]
	s_add_i32 m0, s41, 0xe000
	s_nop 0
	global_load_lds_dwordx4 v196, s[16:17]
	s_waitcnt vmcnt(8) lgkmcnt(0)
	s_barrier
	v_mfma_f32_16x16x32_bf16 v[148:151], v[80:83], v[160:163], v[148:151]
	v_mfma_f32_16x16x32_bf16 v[144:147], v[104:107], v[160:163], v[144:147]
	v_mfma_f32_16x16x32_bf16 v[124:127], v[80:83], v[168:171], v[124:127]
	v_mfma_f32_16x16x32_bf16 v[120:123], v[104:107], v[168:171], v[120:123]
	v_mfma_f32_16x16x32_bf16 v[100:103], v[80:83], v[176:179], v[100:103]
	v_mfma_f32_16x16x32_bf16 v[96:99], v[104:107], v[176:179], v[96:99]
	v_mfma_f32_16x16x32_bf16 v[76:79], v[80:83], v[198:201], v[76:79]
	v_mfma_f32_16x16x32_bf16 v[72:75], v[104:107], v[198:201], v[72:75]
	v_mfma_f32_16x16x32_bf16 v[148:151], v[84:87], v[164:167], v[148:151]
	v_mfma_f32_16x16x32_bf16 v[144:147], v[108:111], v[164:167], v[144:147]
	v_mfma_f32_16x16x32_bf16 v[124:127], v[84:87], v[172:175], v[124:127]
	v_mfma_f32_16x16x32_bf16 v[120:123], v[108:111], v[172:175], v[120:123]
	v_mfma_f32_16x16x32_bf16 v[100:103], v[84:87], v[180:183], v[100:103]
	v_mfma_f32_16x16x32_bf16 v[96:99], v[108:111], v[180:183], v[96:99]
	v_mfma_f32_16x16x32_bf16 v[76:79], v[84:87], v[202:205], v[76:79]
	v_mfma_f32_16x16x32_bf16 v[72:75], v[108:111], v[202:205], v[72:75]
	v_mfma_f32_16x16x32_bf16 v[140:143], v[128:131], v[160:163], v[140:143]
	v_mfma_f32_16x16x32_bf16 v[132:135], v[152:155], v[160:163], v[132:135]
	v_mfma_f32_16x16x32_bf16 v[116:119], v[128:131], v[168:171], v[116:119]
	v_mfma_f32_16x16x32_bf16 v[112:115], v[152:155], v[168:171], v[112:115]
	v_mfma_f32_16x16x32_bf16 v[92:95], v[128:131], v[176:179], v[92:95]
	v_mfma_f32_16x16x32_bf16 v[88:91], v[152:155], v[176:179], v[88:91]
	v_mfma_f32_16x16x32_bf16 v[68:71], v[128:131], v[198:201], v[68:71]
	v_mfma_f32_16x16x32_bf16 v[64:67], v[152:155], v[198:201], v[64:67]
	v_mfma_f32_16x16x32_bf16 v[140:143], v[136:139], v[164:167], v[140:143]
	v_mfma_f32_16x16x32_bf16 v[132:135], v[156:159], v[164:167], v[132:135]
	v_mfma_f32_16x16x32_bf16 v[116:119], v[136:139], v[172:175], v[116:119]
	v_mfma_f32_16x16x32_bf16 v[112:115], v[156:159], v[172:175], v[112:115]
	v_mfma_f32_16x16x32_bf16 v[92:95], v[136:139], v[180:183], v[92:95]
	v_mfma_f32_16x16x32_bf16 v[88:91], v[156:159], v[180:183], v[88:91]
	v_mfma_f32_16x16x32_bf16 v[68:71], v[136:139], v[202:205], v[68:71]
	v_mfma_f32_16x16x32_bf16 v[64:67], v[156:159], v[202:205], v[64:67]
	s_barrier
; #define PG8_STAGE(bufoff, gbase, voff) do { _Pragma("unroll") for (int _i = 0; _i < 2; ++_i) \
;         __builtin_amdgcn_global_load_lds((const unsigned*)((const char*)(gbase) + (voff)[_i]), (PG8_LAS unsigned*)(lds + (bufoff) + ldsw + _i * 8192), 16, 0, 0); } while (0)
; #define PG8_LDA(dst, b, h) do { _Pragma("unroll") for (int m = 0; m < 4; ++m) _Pragma("unroll") for (int k = 0; k < 2; ++k) dst[m][k] = *(const PG8_LAS bf16x8*)(lds + PG8_SA(b, h) + aoff + m * 2048 + k * 1024); } while (0)
; #define PG8_LDB(dst, b, h) do { _Pragma("unroll") for (int n = 0; n < 2; ++n) _Pragma("unroll") for (int k = 0; k < 2; ++k) dst[n][k] = *(const PG8_LAS bf16x8*)(lds + PG8_SB(b, h) + boff + n * 2048 + k * 1024); } while (0)
; #define PG8_MMA(ai, bj, At, Bt) do { __builtin_amdgcn_s_setprio(1); _Pragma("unroll") for (int m = 0; m < 4; ++m) _Pragma("unroll") for (int n = 0; n < 2; ++n) _Pragma("unroll") for (int k = 0; k < 2; ++k) \
;         acc[ai][bj][m][n] = __builtin_amdgcn_mfma_f32_16x16x32_bf16(Bt[n][k], At[m][k], acc[ai][bj][m][n], 0, 0, 0); __builtin_amdgcn_s_setprio(0); } while (0)
; #define PG8_WAIT_V(n) asm volatile("s_waitcnt vmcnt(" #n ")" ::: "memory")
; #define PG8_WAIT_L(n) asm volatile("s_waitcnt lgkmcnt(" #n ")" ::: "memory")
; #define PG8_BAR __builtin_amdgcn_s_barrier()
; #define PG8_SCHED __builtin_amdgcn_sched_barrier(0)
; template <class Epi, class Sched, bool ALIGN_EPI = false, bool SP2 = false>
; __device__ __forceinline__ void gemm_phase(PG8_LAS unsigned char* lds, const Gemm g, const Sched& S, const Epi& E) {
;     ...
;             PG8_LDA(At, 0, 1); PG8_STAGE(PG8_SB(0, 0), b2, voffB); PG8_STAGE(PG8_SB(0, 1), b2 + hstep, voffB); PG8_STAGE(PG8_SA(0, 0), a2, voffA);
;             PG8_WAIT_V(8); PG8_WAIT_L(0); PG8_BAR; PG8_MMA(1, 0, At, B0); PG8_MMA(1, 1, At, B1); PG8_BAR; PG8_SCHED;
;             PG8_LDB(B0, 1, 0); PG8_LDB(B1, 1, 1); PG8_SCHED; PG8_LDA(At, 1, 0); PG8_STAGE(PG8_SA(0, 1), a2 + hstep, voffA);
;             PG8_WAIT_V(8); PG8_WAIT_L(0); PG8_BAR; PG8_MMA(0, 0, At, B0); PG8_MMA(0, 1, At, B1); PG8_BAR; PG8_SCHED;
	s_add_i32 s76, s76, s39
	s_mov_b32 m0, s76
	ds_read_b128 v[160:163], v207 offset:16384
	ds_read_b128 v[164:167], v207 offset:17408
	ds_read_b128 v[168:171], v207 offset:18432
	ds_read_b128 v[172:175], v207 offset:19456
	ds_read_b128 v[176:179], v207 offset:20480
	ds_read_b128 v[180:183], v207 offset:21504
	ds_read_b128 v[198:201], v207 offset:22528
	ds_read_b128 v[202:205], v207 offset:23552
	global_load_lds_dwordx4 v186, s[20:21]
	s_add_i32 m0, s76, 0x2000
	s_add_u32 s76, s20, 0x4000
	s_addc_u32 s77, s21, 0
	s_add_i32 s78, s78, s39
	global_load_lds_dwordx4 v190, s[20:21]
	s_mov_b32 m0, s78
	s_nop 0
	global_load_lds_dwordx4 v186, s[76:77]
	s_add_i32 m0, s78, 0x2000
	s_nop 0
	global_load_lds_dwordx4 v190, s[76:77]
	s_mov_b32 m0, s41
	s_nop 0
	global_load_lds_dwordx4 v184, s[64:65]
	s_mov_b32 m0, s42
	s_nop 0
	global_load_lds_dwordx4 v188, s[64:65]
	s_waitcnt vmcnt(8) lgkmcnt(0)
	s_barrier
	v_mfma_f32_16x16x32_bf16 v[60:63], v[80:83], v[160:163], v[60:63]
	v_mfma_f32_16x16x32_bf16 v[56:59], v[104:107], v[160:163], v[56:59]
	v_mfma_f32_16x16x32_bf16 v[44:47], v[80:83], v[168:171], v[44:47]
	v_mfma_f32_16x16x32_bf16 v[40:43], v[104:107], v[168:171], v[40:43]
	v_mfma_f32_16x16x32_bf16 v[28:31], v[80:83], v[176:179], v[28:31]
	v_mfma_f32_16x16x32_bf16 v[24:27], v[104:107], v[176:179], v[24:27]
	v_mfma_f32_16x16x32_bf16 v[12:15], v[80:83], v[198:201], v[12:15]
	v_mfma_f32_16x16x32_bf16 v[8:11], v[104:107], v[198:201], v[8:11]
	v_mfma_f32_16x16x32_bf16 v[60:63], v[84:87], v[164:167], v[60:63]
	v_mfma_f32_16x16x32_bf16 v[56:59], v[108:111], v[164:167], v[56:59]
	v_mfma_f32_16x16x32_bf16 v[44:47], v[84:87], v[172:175], v[44:47]
	v_mfma_f32_16x16x32_bf16 v[40:43], v[108:111], v[172:175], v[40:43]
	v_mfma_f32_16x16x32_bf16 v[28:31], v[84:87], v[180:183], v[28:31]
	v_mfma_f32_16x16x32_bf16 v[24:27], v[108:111], v[180:183], v[24:27]
	v_mfma_f32_16x16x32_bf16 v[12:15], v[84:87], v[202:205], v[12:15]
	v_mfma_f32_16x16x32_bf16 v[8:11], v[108:111], v[202:205], v[8:11]
	v_mfma_f32_16x16x32_bf16 v[52:55], v[128:131], v[160:163], v[52:55]
	v_mfma_f32_16x16x32_bf16 v[48:51], v[152:155], v[160:163], v[48:51]
	v_mfma_f32_16x16x32_bf16 v[36:39], v[128:131], v[168:171], v[36:39]
	v_mfma_f32_16x16x32_bf16 v[32:35], v[152:155], v[168:171], v[32:35]
	v_mfma_f32_16x16x32_bf16 v[20:23], v[128:131], v[176:179], v[20:23]
	v_mfma_f32_16x16x32_bf16 v[16:19], v[152:155], v[176:179], v[16:19]
	v_mfma_f32_16x16x32_bf16 v[4:7], v[128:131], v[198:201], v[4:7]
	v_mfma_f32_16x16x32_bf16 v[0:3], v[152:155], v[198:201], v[0:3]
	v_mfma_f32_16x16x32_bf16 v[52:55], v[136:139], v[164:167], v[52:55]
	v_mfma_f32_16x16x32_bf16 v[48:51], v[156:159], v[164:167], v[48:51]
	v_mfma_f32_16x16x32_bf16 v[36:39], v[136:139], v[172:175], v[36:39]
	v_mfma_f32_16x16x32_bf16 v[32:35], v[156:159], v[172:175], v[32:35]
	v_mfma_f32_16x16x32_bf16 v[20:23], v[136:139], v[180:183], v[20:23]
	v_mfma_f32_16x16x32_bf16 v[16:19], v[156:159], v[180:183], v[16:19]
	v_mfma_f32_16x16x32_bf16 v[4:7], v[136:139], v[202:205], v[4:7]
	v_mfma_f32_16x16x32_bf16 v[0:3], v[156:159], v[202:205], v[0:3]
	s_barrier
	s_add_i32 s76, 0, 0x18000
	s_add_i32 s77, 0, 0x1c000
	ds_read_b128 v[80:83], v246 offset:32768
	ds_read_b128 v[84:87], v246 offset:33792
	ds_read_b128 v[104:107], v246 offset:34816
	ds_read_b128 v[108:111], v246 offset:35840
	ds_read_b128 v[128:131], v246 offset:49152
	ds_read_b128 v[136:139], v246 offset:50176
	ds_read_b128 v[152:155], v246 offset:51200
	ds_read_b128 v[156:159], v246 offset:52224
	s_add_u32 s64, s64, 0x4000
	s_addc_u32 s65, s65, 0
	s_mov_b32 m0, s50
	ds_read_b128 v[160:163], v207 offset:32768
	ds_read_b128 v[164:167], v207 offset:33792
	ds_read_b128 v[168:171], v207 offset:34816
	ds_read_b128 v[172:175], v207 offset:35840
	ds_read_b128 v[176:179], v207 offset:36864
	ds_read_b128 v[180:183], v207 offset:37888
	ds_read_b128 v[198:201], v207 offset:38912
	ds_read_b128 v[202:205], v207 offset:39936
	global_load_lds_dwordx4 v184, s[64:65]
	s_mov_b32 m0, s51
	s_nop 0
	global_load_lds_dwordx4 v188, s[64:65]
	s_waitcnt vmcnt(8) lgkmcnt(0)
	s_barrier
; #define PG8_STAGE(bufoff, gbase, voff) do { _Pragma("unroll") for (int _i = 0; _i < 2; ++_i) \
;         __builtin_amdgcn_global_load_lds((const unsigned*)((const char*)(gbase) + (voff)[_i]), (PG8_LAS unsigned*)(lds + (bufoff) + ldsw + _i * 8192), 16, 0, 0); } while (0)
; #define PG8_LDA(dst, b, h) do { _Pragma("unroll") for (int m = 0; m < 4; ++m) _Pragma("unroll") for (int k = 0; k < 2; ++k) dst[m][k] = *(const PG8_LAS bf16x8*)(lds + PG8_SA(b, h) + aoff + m * 2048 + k * 1024); } while (0)
; #define PG8_MMA(ai, bj, At, Bt) do { __builtin_amdgcn_s_setprio(1); _Pragma("unroll") for (int m = 0; m < 4; ++m) _Pragma("unroll") for (int n = 0; n < 2; ++n) _Pragma("unroll") for (int k = 0; k < 2; ++k) \
;         acc[ai][bj][m][n] = __builtin_amdgcn_mfma_f32_16x16x32_bf16(Bt[n][k], At[m][k], acc[ai][bj][m][n], 0, 0, 0); __builtin_amdgcn_s_setprio(0); } while (0)
; #define PG8_WAIT_V(n) asm volatile("s_waitcnt vmcnt(" #n ")" ::: "memory")
; #define PG8_WAIT_L(n) asm volatile("s_waitcnt lgkmcnt(" #n ")" ::: "memory")
; #define PG8_BAR __builtin_amdgcn_s_barrier()
; #define PG8_SCHED __builtin_amdgcn_sched_barrier(0)
; template <class Epi, class Sched, bool ALIGN_EPI = false, bool SP2 = false>
; __device__ __forceinline__ void gemm_phase(PG8_LAS unsigned char* lds, const Gemm g, const Sched& S, const Epi& E) {
;     ...
;             PG8_WAIT_V(8); PG8_WAIT_L(0); PG8_BAR; PG8_MMA(0, 0, At, B0); PG8_MMA(0, 1, At, B1); PG8_BAR; PG8_SCHED;
;             PG8_LDA(At, 1, 1); PG8_STAGE(PG8_SB(1, 0), b3, voffB); PG8_STAGE(PG8_SB(1, 1), b3 + hstep, voffB); PG8_STAGE(PG8_SA(1, 0), a3, voffA);
;             PG8_WAIT_V(8); PG8_WAIT_L(0); PG8_BAR; PG8_MMA(1, 0, At, B0); PG8_MMA(1, 1, At, B1); PG8_BAR; PG8_SCHED;
	v_mfma_f32_16x16x32_bf16 v[148:151], v[80:83], v[160:163], v[148:151]
	v_mfma_f32_16x16x32_bf16 v[144:147], v[104:107], v[160:163], v[144:147]
	v_mfma_f32_16x16x32_bf16 v[124:127], v[80:83], v[168:171], v[124:127]
	v_mfma_f32_16x16x32_bf16 v[120:123], v[104:107], v[168:171], v[120:123]
	v_mfma_f32_16x16x32_bf16 v[100:103], v[80:83], v[176:179], v[100:103]
	v_mfma_f32_16x16x32_bf16 v[96:99], v[104:107], v[176:179], v[96:99]
	v_mfma_f32_16x16x32_bf16 v[76:79], v[80:83], v[198:201], v[76:79]
	v_mfma_f32_16x16x32_bf16 v[72:75], v[104:107], v[198:201], v[72:75]
	v_mfma_f32_16x16x32_bf16 v[148:151], v[84:87], v[164:167], v[148:151]
	v_mfma_f32_16x16x32_bf16 v[144:147], v[108:111], v[164:167], v[144:147]
	v_mfma_f32_16x16x32_bf16 v[124:127], v[84:87], v[172:175], v[124:127]
	v_mfma_f32_16x16x32_bf16 v[120:123], v[108:111], v[172:175], v[120:123]
	v_mfma_f32_16x16x32_bf16 v[100:103], v[84:87], v[180:183], v[100:103]
	v_mfma_f32_16x16x32_bf16 v[96:99], v[108:111], v[180:183], v[96:99]
	v_mfma_f32_16x16x32_bf16 v[76:79], v[84:87], v[202:205], v[76:79]
	v_mfma_f32_16x16x32_bf16 v[72:75], v[108:111], v[202:205], v[72:75]
	v_mfma_f32_16x16x32_bf16 v[140:143], v[128:131], v[160:163], v[140:143]
	v_mfma_f32_16x16x32_bf16 v[132:135], v[152:155], v[160:163], v[132:135]
	v_mfma_f32_16x16x32_bf16 v[116:119], v[128:131], v[168:171], v[116:119]
	v_mfma_f32_16x16x32_bf16 v[112:115], v[152:155], v[168:171], v[112:115]
	v_mfma_f32_16x16x32_bf16 v[92:95], v[128:131], v[176:179], v[92:95]
	v_mfma_f32_16x16x32_bf16 v[88:91], v[152:155], v[176:179], v[88:91]
	v_mfma_f32_16x16x32_bf16 v[68:71], v[128:131], v[198:201], v[68:71]
	v_mfma_f32_16x16x32_bf16 v[64:67], v[152:155], v[198:201], v[64:67]
	v_mfma_f32_16x16x32_bf16 v[140:143], v[136:139], v[164:167], v[140:143]
	v_mfma_f32_16x16x32_bf16 v[132:135], v[156:159], v[164:167], v[132:135]
	v_mfma_f32_16x16x32_bf16 v[116:119], v[136:139], v[172:175], v[116:119]
	v_mfma_f32_16x16x32_bf16 v[112:115], v[156:159], v[172:175], v[112:115]
	v_mfma_f32_16x16x32_bf16 v[92:95], v[136:139], v[180:183], v[92:95]
	v_mfma_f32_16x16x32_bf16 v[88:91], v[156:159], v[180:183], v[88:91]
	v_mfma_f32_16x16x32_bf16 v[68:71], v[136:139], v[202:205], v[68:71]
	v_mfma_f32_16x16x32_bf16 v[64:67], v[156:159], v[202:205], v[64:67]
	s_barrier
	s_add_u32 s64, s20, 0x8000
	s_addc_u32 s65, s21, 0
	s_add_i32 s76, s76, s39
	s_mov_b32 m0, s76
	ds_read_b128 v[160:163], v207 offset:49152
	ds_read_b128 v[164:167], v207 offset:50176
	ds_read_b128 v[168:171], v207 offset:51200
	ds_read_b128 v[172:175], v207 offset:52224
	ds_read_b128 v[176:179], v207 offset:53248
	ds_read_b128 v[180:183], v207 offset:54272
	ds_read_b128 v[198:201], v207 offset:55296
	ds_read_b128 v[202:205], v207 offset:56320
	global_load_lds_dwordx4 v186, s[64:65]
	s_add_i32 m0, s76, 0x2000
	s_add_u32 s20, s20, 0xc000
	s_addc_u32 s21, s21, 0
	s_add_i32 s91, s77, s39
	global_load_lds_dwordx4 v190, s[64:65]
	s_mov_b32 m0, s91
	s_nop 0
	global_load_lds_dwordx4 v186, s[20:21]
	s_add_i32 m0, s91, 0x2000
	s_nop 0
	global_load_lds_dwordx4 v190, s[20:21]
	s_mov_b32 m0, s56
	s_nop 0
	global_load_lds_dwordx4 v184, s[18:19]
	s_mov_b32 m0, s57
	s_nop 0
	global_load_lds_dwordx4 v188, s[18:19]
	s_waitcnt vmcnt(8) lgkmcnt(0)
	s_barrier
	v_mfma_f32_16x16x32_bf16 v[60:63], v[80:83], v[160:163], v[60:63]
	v_mfma_f32_16x16x32_bf16 v[56:59], v[104:107], v[160:163], v[56:59]
	v_mfma_f32_16x16x32_bf16 v[44:47], v[80:83], v[168:171], v[44:47]
	v_mfma_f32_16x16x32_bf16 v[40:43], v[104:107], v[168:171], v[40:43]
	v_mfma_f32_16x16x32_bf16 v[28:31], v[80:83], v[176:179], v[28:31]
	v_mfma_f32_16x16x32_bf16 v[24:27], v[104:107], v[176:179], v[24:27]
	v_mfma_f32_16x16x32_bf16 v[12:15], v[80:83], v[198:201], v[12:15]
	v_mfma_f32_16x16x32_bf16 v[8:11], v[104:107], v[198:201], v[8:11]
	v_mfma_f32_16x16x32_bf16 v[60:63], v[84:87], v[164:167], v[60:63]
	v_mfma_f32_16x16x32_bf16 v[56:59], v[108:111], v[164:167], v[56:59]
	v_mfma_f32_16x16x32_bf16 v[44:47], v[84:87], v[172:175], v[44:47]
	v_mfma_f32_16x16x32_bf16 v[40:43], v[108:111], v[172:175], v[40:43]
	v_mfma_f32_16x16x32_bf16 v[28:31], v[84:87], v[180:183], v[28:31]
	v_mfma_f32_16x16x32_bf16 v[24:27], v[108:111], v[180:183], v[24:27]
	v_mfma_f32_16x16x32_bf16 v[12:15], v[84:87], v[202:205], v[12:15]
	v_mfma_f32_16x16x32_bf16 v[8:11], v[108:111], v[202:205], v[8:11]
	v_mfma_f32_16x16x32_bf16 v[52:55], v[128:131], v[160:163], v[52:55]
	v_mfma_f32_16x16x32_bf16 v[48:51], v[152:155], v[160:163], v[48:51]
	v_mfma_f32_16x16x32_bf16 v[36:39], v[128:131], v[168:171], v[36:39]
	v_mfma_f32_16x16x32_bf16 v[32:35], v[152:155], v[168:171], v[32:35]
	v_mfma_f32_16x16x32_bf16 v[20:23], v[128:131], v[176:179], v[20:23]
	v_mfma_f32_16x16x32_bf16 v[16:19], v[152:155], v[176:179], v[16:19]
	v_mfma_f32_16x16x32_bf16 v[4:7], v[128:131], v[198:201], v[4:7]
	v_mfma_f32_16x16x32_bf16 v[0:3], v[152:155], v[198:201], v[0:3]
	v_mfma_f32_16x16x32_bf16 v[52:55], v[136:139], v[164:167], v[52:55]
	v_mfma_f32_16x16x32_bf16 v[48:51], v[156:159], v[164:167], v[48:51]
	v_mfma_f32_16x16x32_bf16 v[36:39], v[136:139], v[172:175], v[36:39]
	v_mfma_f32_16x16x32_bf16 v[32:35], v[156:159], v[172:175], v[32:35]
	v_mfma_f32_16x16x32_bf16 v[20:23], v[136:139], v[180:183], v[20:23]
	v_mfma_f32_16x16x32_bf16 v[16:19], v[156:159], v[180:183], v[16:19]
	v_mfma_f32_16x16x32_bf16 v[4:7], v[136:139], v[202:205], v[4:7]
	v_mfma_f32_16x16x32_bf16 v[0:3], v[156:159], v[202:205], v[0:3]
	s_barrier
	s_add_u32 s16, s16, 0x10000
	s_addc_u32 s17, s17, 0
	s_add_u32 s66, s66, 0x10000
	s_addc_u32 s67, s67, 0
	s_cmp_ge_u32 s75, s53
	s_mov_b32 s18, s75
	s_cbranch_scc0 .LBB0_1322
	s_and_b64 vcc, exec, s[12:13]
	s_cbranch_vccz .LBB0_1325
	s_barrier

; #define PG8_STAGE(bufoff, gbase, voff) do { _Pragma("unroll") for (int _i = 0; _i < 2; ++_i) \
;         __builtin_amdgcn_global_load_lds((const unsigned*)((const char*)(gbase) + (voff)[_i]), (PG8_LAS unsigned*)(lds + (bufoff) + ldsw + _i * 8192), 16, 0, 0); } while (0)
; #define PG8_LDA(dst, b, h) do { _Pragma("unroll") for (int m = 0; m < 4; ++m) _Pragma("unroll") for (int k = 0; k < 2; ++k) dst[m][k] = *(const PG8_LAS bf16x8*)(lds + PG8_SA(b, h) + aoff + m * 2048 + k * 1024); } while (0)
; #define PG8_LDB(dst, b, h) do { _Pragma("unroll") for (int n = 0; n < 2; ++n) _Pragma("unroll") for (int k = 0; k < 2; ++k) dst[n][k] = *(const PG8_LAS bf16x8*)(lds + PG8_SB(b, h) + boff + n * 2048 + k * 1024); } while (0)
; #define PG8_WAIT_V(n) asm volatile("s_waitcnt vmcnt(" #n ")" ::: "memory")
; #define PG8_WAIT_L(n) asm volatile("s_waitcnt lgkmcnt(" #n ")" ::: "memory")
; #define PG8_BAR __builtin_amdgcn_s_barrier()
; #define PG8_SCHED __builtin_amdgcn_sched_barrier(0)
; template <class Epi, class Sched, bool ALIGN_EPI = false, bool SP2 = false>
; __device__ __forceinline__ void gemm_phase(PG8_LAS unsigned char* lds, const Gemm g, const Sched& S, const Epi& E) {
;     ...
;         for (int t = 0; t < nt; t += 2) {
;             const bool last = (t == nt - 2);
;             const char* a1 = cA + (size_t)(t + 1) * kstep;
;             const char* a2 = last ? nA : cA + (size_t)(t + 2) * kstep; const char* b2 = last ? nB : cB + (size_t)(t + 2) * kstep;
;             const char* a3 = a2 + kstep; const char* b3 = b2 + kstep;
;             if (last && has_next) S.a_ready(nxt);
;             if constexpr (SP2) {
;             PG8_LDB(B0, 0, 0); PG8_LDB(B1, 0, 1); PG8_SCHED; PG8_LDA(At, 0, 0); PG8_STAGE(PG8_SA(1, 1), a1 + hstep, voffA);
;             PG8_WAIT_V(8); PG8_WAIT_L(0); PG8_BAR; PG8_MMA(0, 0, At, B0); PG8_MMA(0, 1, At, B1); PG8_BAR; PG8_SCHED;
;             PG8_LDA(At, 0, 1); PG8_STAGE(PG8_SB(0, 0), b2, voffB); PG8_STAGE(PG8_SB(0, 1), b2 + hstep, voffB); PG8_STAGE(PG8_SA(0, 0), a2, voffA);
;     ...
; #pragma unroll
;         for (int a = 0; a < 2; ++a)
; #pragma unroll
;             for (int b = 0; b < 2; ++b)
; #pragma unroll
;                 for (int m = 0; m < 4; ++m)
; #pragma unroll
;                     for (int n = 0; n < 2; ++n) acc[a][b][m][n] = (f32x4){0.f, 0.f, 0.f, 0.f};
;         cur = nxt; cA = nA; cB = nB; ++ui;
.LBB0_1355:
	s_ashr_i32 s11, s10, 31
	s_lshl_b64 s[12:13], s[10:11], 19
	s_add_u32 s12, s22, s12
	s_addc_u32 s13, s23, s13
	s_and_b64 s[14:15], s[2:3], exec
	s_cselect_b32 s11, s13, s19
	s_cselect_b32 s40, s12, s18
	s_ashr_i32 s9, s8, 31
	s_lshl_b64 s[14:15], s[8:9], 19
	s_add_u32 s14, s27, s14
	s_addc_u32 s15, s28, s15
	s_and_b64 s[62:63], s[2:3], exec
	s_cselect_b32 s9, s15, s21
	s_cselect_b32 s61, s14, s20
	s_add_u32 s18, s18, 0xc000
	s_addc_u32 s19, s19, 0
	s_add_u32 s66, s20, 0x10000
	v_mov_b32_e32 v0, 0
	s_addc_u32 s67, s21, 0
	s_mov_b32 s68, -2
	v_mov_b32_e32 v1, v0
	v_mov_b32_e32 v2, v0
	v_mov_b32_e32 v3, v0
	v_mov_b32_e32 v4, v0
	v_mov_b32_e32 v5, v0
	v_mov_b32_e32 v6, v0
	v_mov_b32_e32 v7, v0
	v_mov_b32_e32 v16, v0
	v_mov_b32_e32 v17, v0
	v_mov_b32_e32 v18, v0
	v_mov_b32_e32 v19, v0
	v_mov_b32_e32 v20, v0
	v_mov_b32_e32 v21, v0
	v_mov_b32_e32 v22, v0
	v_mov_b32_e32 v23, v0
	v_mov_b32_e32 v32, v0
	v_mov_b32_e32 v33, v0
	v_mov_b32_e32 v34, v0
	v_mov_b32_e32 v35, v0
	v_mov_b32_e32 v36, v0
	v_mov_b32_e32 v37, v0
	v_mov_b32_e32 v38, v0
	v_mov_b32_e32 v39, v0
	v_mov_b32_e32 v48, v0
	v_mov_b32_e32 v49, v0
	v_mov_b32_e32 v50, v0
	v_mov_b32_e32 v51, v0
	v_mov_b32_e32 v52, v0
	v_mov_b32_e32 v53, v0
	v_mov_b32_e32 v54, v0
	v_mov_b32_e32 v55, v0
	v_mov_b32_e32 v8, v0
	v_mov_b32_e32 v9, v0
	v_mov_b32_e32 v10, v0
	v_mov_b32_e32 v11, v0
	v_mov_b32_e32 v12, v0
	v_mov_b32_e32 v13, v0
	v_mov_b32_e32 v14, v0
	v_mov_b32_e32 v15, v0
	v_mov_b32_e32 v24, v0
	v_mov_b32_e32 v25, v0
	v_mov_b32_e32 v26, v0
	v_mov_b32_e32 v27, v0
	v_mov_b32_e32 v28, v0
	v_mov_b32_e32 v29, v0
	v_mov_b32_e32 v30, v0
	v_mov_b32_e32 v31, v0
	v_mov_b32_e32 v40, v0
	v_mov_b32_e32 v41, v0
	v_mov_b32_e32 v42, v0
	v_mov_b32_e32 v43, v0
	v_mov_b32_e32 v44, v0
	v_mov_b32_e32 v45, v0
	v_mov_b32_e32 v46, v0
	v_mov_b32_e32 v47, v0
	v_mov_b32_e32 v56, v0
	v_mov_b32_e32 v57, v0
	v_mov_b32_e32 v58, v0
	v_mov_b32_e32 v59, v0
	v_mov_b32_e32 v60, v0
	v_mov_b32_e32 v61, v0
	v_mov_b32_e32 v62, v0
	v_mov_b32_e32 v63, v0
	v_mov_b32_e32 v64, v0
	v_mov_b32_e32 v65, v0
	v_mov_b32_e32 v66, v0
	v_mov_b32_e32 v67, v0
	v_mov_b32_e32 v68, v0
	v_mov_b32_e32 v69, v0
	v_mov_b32_e32 v70, v0
	v_mov_b32_e32 v71, v0
	v_mov_b32_e32 v80, v0
	v_mov_b32_e32 v81, v0
	v_mov_b32_e32 v82, v0
	v_mov_b32_e32 v83, v0
	v_mov_b32_e32 v84, v0
	v_mov_b32_e32 v85, v0
	v_mov_b32_e32 v86, v0
	v_mov_b32_e32 v87, v0
	v_mov_b32_e32 v96, v0
	v_mov_b32_e32 v97, v0
	v_mov_b32_e32 v98, v0
	v_mov_b32_e32 v99, v0
	v_mov_b32_e32 v100, v0
	v_mov_b32_e32 v101, v0
	v_mov_b32_e32 v102, v0
	v_mov_b32_e32 v103, v0
	v_mov_b32_e32 v112, v0
	v_mov_b32_e32 v113, v0
	v_mov_b32_e32 v114, v0
	v_mov_b32_e32 v115, v0
	v_mov_b32_e32 v116, v0
	v_mov_b32_e32 v117, v0
	v_mov_b32_e32 v118, v0
	v_mov_b32_e32 v119, v0
	v_mov_b32_e32 v72, v0
	v_mov_b32_e32 v73, v0
	v_mov_b32_e32 v74, v0
	v_mov_b32_e32 v75, v0
	v_mov_b32_e32 v76, v0
	v_mov_b32_e32 v77, v0
	v_mov_b32_e32 v78, v0
	v_mov_b32_e32 v79, v0
	v_mov_b32_e32 v88, v0
	v_mov_b32_e32 v89, v0
	v_mov_b32_e32 v90, v0
	v_mov_b32_e32 v91, v0
	v_mov_b32_e32 v92, v0
	v_mov_b32_e32 v93, v0
	v_mov_b32_e32 v94, v0
	v_mov_b32_e32 v95, v0
	v_mov_b32_e32 v104, v0
	v_mov_b32_e32 v105, v0
	v_mov_b32_e32 v106, v0
	v_mov_b32_e32 v107, v0
	v_mov_b32_e32 v108, v0
	v_mov_b32_e32 v109, v0
	v_mov_b32_e32 v110, v0
	v_mov_b32_e32 v111, v0
	v_mov_b32_e32 v120, v0
	v_mov_b32_e32 v121, v0
	v_mov_b32_e32 v122, v0
	v_mov_b32_e32 v123, v0
	v_mov_b32_e32 v124, v0
	v_mov_b32_e32 v125, v0
	v_mov_b32_e32 v126, v0
	v_mov_b32_e32 v127, v0
	v_add_u32_e32 v246, 0x10000, v162
.LBB0_1356:
	s_add_u32 s20, s18, 0x4000
	s_addc_u32 s21, s19, 0
	s_cmp_eq_u32 s68, 12
	s_cselect_b32 s64, s40, s20
	s_cselect_b32 s65, s11, s21
	s_cselect_b32 s62, s61, s66
	s_cselect_b32 s63, s9, s67
	s_add_u32 s20, s64, 0x8000
	s_addc_u32 s21, s65, 0
	s_add_i32 s69, 0, 0x10000
	s_add_i32 s72, 0, 0x14000
	ds_read_b128 v[128:131], v246
	ds_read_b128 v[132:135], v246 offset:1024
	ds_read_b128 v[136:139], v246 offset:2048
	ds_read_b128 v[140:143], v246 offset:3072
	ds_read_b128 v[156:159], v246 offset:16384
	ds_read_b128 v[164:167], v246 offset:17408
	ds_read_b128 v[168:171], v246 offset:18432
	ds_read_b128 v[172:175], v246 offset:19456
	s_add_i32 m0, s37, 0xc000
	ds_read_b128 v[176:179], v163
	ds_read_b128 v[180:183], v163 offset:1024
	ds_read_b128 v[184:187], v163 offset:2048
	ds_read_b128 v[188:191], v163 offset:3072
	ds_read_b128 v[192:195], v163 offset:4096
	ds_read_b128 v[196:199], v163 offset:5120
	ds_read_b128 v[200:203], v163 offset:6144
	ds_read_b128 v[204:207], v163 offset:7168
	global_load_lds_dwordx4 v152, s[18:19]
	s_add_i32 m0, s37, 0xe000
	s_nop 0
	global_load_lds_dwordx4 v154, s[18:19]
	s_waitcnt vmcnt(8) lgkmcnt(0)
	s_barrier
; #define PG8_STAGE(bufoff, gbase, voff) do { _Pragma("unroll") for (int _i = 0; _i < 2; ++_i) \
;         __builtin_amdgcn_global_load_lds((const unsigned*)((const char*)(gbase) + (voff)[_i]), (PG8_LAS unsigned*)(lds + (bufoff) + ldsw + _i * 8192), 16, 0, 0); } while (0)
; #define PG8_LDA(dst, b, h) do { _Pragma("unroll") for (int m = 0; m < 4; ++m) _Pragma("unroll") for (int k = 0; k < 2; ++k) dst[m][k] = *(const PG8_LAS bf16x8*)(lds + PG8_SA(b, h) + aoff + m * 2048 + k * 1024); } while (0)
; #define PG8_MMA(ai, bj, At, Bt) do { __builtin_amdgcn_s_setprio(1); _Pragma("unroll") for (int m = 0; m < 4; ++m) _Pragma("unroll") for (int n = 0; n < 2; ++n) _Pragma("unroll") for (int k = 0; k < 2; ++k) \
;         acc[ai][bj][m][n] = __builtin_amdgcn_mfma_f32_16x16x32_bf16(Bt[n][k], At[m][k], acc[ai][bj][m][n], 0, 0, 0); __builtin_amdgcn_s_setprio(0); } while (0)
; #define PG8_WAIT_V(n) asm volatile("s_waitcnt vmcnt(" #n ")" ::: "memory")
; #define PG8_WAIT_L(n) asm volatile("s_waitcnt lgkmcnt(" #n ")" ::: "memory")
; #define PG8_BAR __builtin_amdgcn_s_barrier()
; #define PG8_SCHED __builtin_amdgcn_sched_barrier(0)
; template <class Epi, class Sched, bool ALIGN_EPI = false, bool SP2 = false>
; __device__ __forceinline__ void gemm_phase(PG8_LAS unsigned char* lds, const Gemm g, const Sched& S, const Epi& E) {
;     ...
;             PG8_WAIT_V(8); PG8_WAIT_L(0); PG8_BAR; PG8_MMA(0, 0, At, B0); PG8_MMA(0, 1, At, B1); PG8_BAR; PG8_SCHED;
;             PG8_LDA(At, 0, 1); PG8_STAGE(PG8_SB(0, 0), b2, voffB); PG8_STAGE(PG8_SB(0, 1), b2 + hstep, voffB); PG8_STAGE(PG8_SA(0, 0), a2, voffA);
;             PG8_WAIT_V(8); PG8_WAIT_L(0); PG8_BAR; PG8_MMA(1, 0, At, B0); PG8_MMA(1, 1, At, B1); PG8_BAR; PG8_SCHED;
	v_mfma_f32_16x16x32_bf16 v[124:127], v[128:131], v[176:179], v[124:127]
	v_mfma_f32_16x16x32_bf16 v[120:123], v[136:139], v[176:179], v[120:123]
	v_mfma_f32_16x16x32_bf16 v[108:111], v[128:131], v[184:187], v[108:111]
	v_mfma_f32_16x16x32_bf16 v[104:107], v[136:139], v[184:187], v[104:107]
	v_mfma_f32_16x16x32_bf16 v[92:95], v[128:131], v[192:195], v[92:95]
	v_mfma_f32_16x16x32_bf16 v[88:91], v[136:139], v[192:195], v[88:91]
	v_mfma_f32_16x16x32_bf16 v[76:79], v[128:131], v[200:203], v[76:79]
	v_mfma_f32_16x16x32_bf16 v[72:75], v[136:139], v[200:203], v[72:75]
	v_mfma_f32_16x16x32_bf16 v[124:127], v[132:135], v[180:183], v[124:127]
	v_mfma_f32_16x16x32_bf16 v[120:123], v[140:143], v[180:183], v[120:123]
	v_mfma_f32_16x16x32_bf16 v[108:111], v[132:135], v[188:191], v[108:111]
	v_mfma_f32_16x16x32_bf16 v[104:107], v[140:143], v[188:191], v[104:107]
	v_mfma_f32_16x16x32_bf16 v[92:95], v[132:135], v[196:199], v[92:95]
	v_mfma_f32_16x16x32_bf16 v[88:91], v[140:143], v[196:199], v[88:91]
	v_mfma_f32_16x16x32_bf16 v[76:79], v[132:135], v[204:207], v[76:79]
	v_mfma_f32_16x16x32_bf16 v[72:75], v[140:143], v[204:207], v[72:75]
	v_mfma_f32_16x16x32_bf16 v[116:119], v[156:159], v[176:179], v[116:119]
	v_mfma_f32_16x16x32_bf16 v[112:115], v[168:171], v[176:179], v[112:115]
	v_mfma_f32_16x16x32_bf16 v[100:103], v[156:159], v[184:187], v[100:103]
	v_mfma_f32_16x16x32_bf16 v[96:99], v[168:171], v[184:187], v[96:99]
	v_mfma_f32_16x16x32_bf16 v[84:87], v[156:159], v[192:195], v[84:87]
	v_mfma_f32_16x16x32_bf16 v[80:83], v[168:171], v[192:195], v[80:83]
	v_mfma_f32_16x16x32_bf16 v[68:71], v[156:159], v[200:203], v[68:71]
	v_mfma_f32_16x16x32_bf16 v[64:67], v[168:171], v[200:203], v[64:67]
	v_mfma_f32_16x16x32_bf16 v[116:119], v[164:167], v[180:183], v[116:119]
	v_mfma_f32_16x16x32_bf16 v[112:115], v[172:175], v[180:183], v[112:115]
	v_mfma_f32_16x16x32_bf16 v[100:103], v[164:167], v[188:191], v[100:103]
	v_mfma_f32_16x16x32_bf16 v[96:99], v[172:175], v[188:191], v[96:99]
	v_mfma_f32_16x16x32_bf16 v[84:87], v[164:167], v[196:199], v[84:87]
	v_mfma_f32_16x16x32_bf16 v[80:83], v[172:175], v[196:199], v[80:83]
	v_mfma_f32_16x16x32_bf16 v[68:71], v[164:167], v[204:207], v[68:71]
	v_mfma_f32_16x16x32_bf16 v[64:67], v[172:175], v[204:207], v[64:67]
	s_barrier
	s_add_i32 s69, s69, s30
	s_mov_b32 m0, s69
	ds_read_b128 v[176:179], v163 offset:16384
	ds_read_b128 v[180:183], v163 offset:17408
	ds_read_b128 v[184:187], v163 offset:18432
	ds_read_b128 v[188:191], v163 offset:19456
	ds_read_b128 v[192:195], v163 offset:20480
	ds_read_b128 v[196:199], v163 offset:21504
	ds_read_b128 v[200:203], v163 offset:22528
	ds_read_b128 v[204:207], v163 offset:23552
	global_load_lds_dwordx4 v148, s[62:63]
	s_add_i32 m0, s69, 0x2000
	s_add_u32 s70, s62, 0x4000
	s_addc_u32 s71, s63, 0
	s_add_i32 s69, s72, s30
	global_load_lds_dwordx4 v144, s[62:63]
	s_mov_b32 m0, s69
	s_nop 0
	global_load_lds_dwordx4 v148, s[70:71]
	s_add_i32 m0, s69, 0x2000
	s_nop 0
	global_load_lds_dwordx4 v144, s[70:71]
	s_mov_b32 m0, s37
	s_nop 0
	global_load_lds_dwordx4 v150, s[64:65]
	s_mov_b32 m0, s39
	s_nop 0
	global_load_lds_dwordx4 v146, s[64:65]
	s_waitcnt vmcnt(8) lgkmcnt(0)
	s_barrier
	v_mfma_f32_16x16x32_bf16 v[60:63], v[128:131], v[176:179], v[60:63]
	v_mfma_f32_16x16x32_bf16 v[56:59], v[136:139], v[176:179], v[56:59]
	v_mfma_f32_16x16x32_bf16 v[44:47], v[128:131], v[184:187], v[44:47]
	v_mfma_f32_16x16x32_bf16 v[40:43], v[136:139], v[184:187], v[40:43]
	v_mfma_f32_16x16x32_bf16 v[28:31], v[128:131], v[192:195], v[28:31]
	v_mfma_f32_16x16x32_bf16 v[24:27], v[136:139], v[192:195], v[24:27]
	v_mfma_f32_16x16x32_bf16 v[12:15], v[128:131], v[200:203], v[12:15]
	v_mfma_f32_16x16x32_bf16 v[8:11], v[136:139], v[200:203], v[8:11]
	v_mfma_f32_16x16x32_bf16 v[60:63], v[132:135], v[180:183], v[60:63]
	v_mfma_f32_16x16x32_bf16 v[56:59], v[140:143], v[180:183], v[56:59]
	v_mfma_f32_16x16x32_bf16 v[44:47], v[132:135], v[188:191], v[44:47]
	v_mfma_f32_16x16x32_bf16 v[40:43], v[140:143], v[188:191], v[40:43]
	v_mfma_f32_16x16x32_bf16 v[28:31], v[132:135], v[196:199], v[28:31]
	v_mfma_f32_16x16x32_bf16 v[24:27], v[140:143], v[196:199], v[24:27]
	v_mfma_f32_16x16x32_bf16 v[12:15], v[132:135], v[204:207], v[12:15]
	v_mfma_f32_16x16x32_bf16 v[8:11], v[140:143], v[204:207], v[8:11]
	v_mfma_f32_16x16x32_bf16 v[52:55], v[156:159], v[176:179], v[52:55]
	v_mfma_f32_16x16x32_bf16 v[48:51], v[168:171], v[176:179], v[48:51]
	v_mfma_f32_16x16x32_bf16 v[36:39], v[156:159], v[184:187], v[36:39]
	v_mfma_f32_16x16x32_bf16 v[32:35], v[168:171], v[184:187], v[32:35]
	v_mfma_f32_16x16x32_bf16 v[20:23], v[156:159], v[192:195], v[20:23]
	v_mfma_f32_16x16x32_bf16 v[16:19], v[168:171], v[192:195], v[16:19]
	v_mfma_f32_16x16x32_bf16 v[4:7], v[156:159], v[200:203], v[4:7]
	v_mfma_f32_16x16x32_bf16 v[0:3], v[168:171], v[200:203], v[0:3]
	v_mfma_f32_16x16x32_bf16 v[52:55], v[164:167], v[180:183], v[52:55]
	v_mfma_f32_16x16x32_bf16 v[48:51], v[172:175], v[180:183], v[48:51]
	v_mfma_f32_16x16x32_bf16 v[36:39], v[164:167], v[188:191], v[36:39]
	v_mfma_f32_16x16x32_bf16 v[32:35], v[172:175], v[188:191], v[32:35]
	v_mfma_f32_16x16x32_bf16 v[20:23], v[164:167], v[196:199], v[20:23]
	v_mfma_f32_16x16x32_bf16 v[16:19], v[172:175], v[196:199], v[16:19]
	v_mfma_f32_16x16x32_bf16 v[4:7], v[164:167], v[204:207], v[4:7]
	v_mfma_f32_16x16x32_bf16 v[0:3], v[172:175], v[204:207], v[0:3]
	s_barrier
; #define PG8_STAGE(bufoff, gbase, voff) do { _Pragma("unroll") for (int _i = 0; _i < 2; ++_i) \
;         __builtin_amdgcn_global_load_lds((const unsigned*)((const char*)(gbase) + (voff)[_i]), (PG8_LAS unsigned*)(lds + (bufoff) + ldsw + _i * 8192), 16, 0, 0); } while (0)
; #define PG8_LDA(dst, b, h) do { _Pragma("unroll") for (int m = 0; m < 4; ++m) _Pragma("unroll") for (int k = 0; k < 2; ++k) dst[m][k] = *(const PG8_LAS bf16x8*)(lds + PG8_SA(b, h) + aoff + m * 2048 + k * 1024); } while (0)
; #define PG8_LDB(dst, b, h) do { _Pragma("unroll") for (int n = 0; n < 2; ++n) _Pragma("unroll") for (int k = 0; k < 2; ++k) dst[n][k] = *(const PG8_LAS bf16x8*)(lds + PG8_SB(b, h) + boff + n * 2048 + k * 1024); } while (0)
; #define PG8_MMA(ai, bj, At, Bt) do { __builtin_amdgcn_s_setprio(1); _Pragma("unroll") for (int m = 0; m < 4; ++m) _Pragma("unroll") for (int n = 0; n < 2; ++n) _Pragma("unroll") for (int k = 0; k < 2; ++k) \
;         acc[ai][bj][m][n] = __builtin_amdgcn_mfma_f32_16x16x32_bf16(Bt[n][k], At[m][k], acc[ai][bj][m][n], 0, 0, 0); __builtin_amdgcn_s_setprio(0); } while (0)
; #define PG8_WAIT_V(n) asm volatile("s_waitcnt vmcnt(" #n ")" ::: "memory")
; #define PG8_WAIT_L(n) asm volatile("s_waitcnt lgkmcnt(" #n ")" ::: "memory")
; #define PG8_BAR __builtin_amdgcn_s_barrier()
; #define PG8_SCHED __builtin_amdgcn_sched_barrier(0)
; template <class Epi, class Sched, bool ALIGN_EPI = false, bool SP2 = false>
; __device__ __forceinline__ void gemm_phase(PG8_LAS unsigned char* lds, const Gemm g, const Sched& S, const Epi& E) {
;     ...
;             PG8_LDB(B0, 1, 0); PG8_LDB(B1, 1, 1); PG8_SCHED; PG8_LDA(At, 1, 0); PG8_STAGE(PG8_SA(0, 1), a2 + hstep, voffA);
;             PG8_WAIT_V(8); PG8_WAIT_L(0); PG8_BAR; PG8_MMA(0, 0, At, B0); PG8_MMA(0, 1, At, B1); PG8_BAR; PG8_SCHED;
;             PG8_LDA(At, 1, 1); PG8_STAGE(PG8_SB(1, 0), b3, voffB); PG8_STAGE(PG8_SB(1, 1), b3 + hstep, voffB); PG8_STAGE(PG8_SA(1, 0), a3, voffA);
;             PG8_WAIT_V(8); PG8_WAIT_L(0); PG8_BAR; PG8_MMA(1, 0, At, B0); PG8_MMA(1, 1, At, B1); PG8_BAR; PG8_SCHED;
;     ...
;         if constexpr (ALIGN_EPI) { if (wr == 0) PG8_BAR; }
	s_add_i32 s69, 0, 0x18000
	s_add_i32 s70, 0, 0x1c000
	ds_read_b128 v[128:131], v246 offset:32768
	ds_read_b128 v[132:135], v246 offset:33792
	ds_read_b128 v[136:139], v246 offset:34816
	ds_read_b128 v[140:143], v246 offset:35840
	ds_read_b128 v[156:159], v246 offset:49152
	ds_read_b128 v[164:167], v246 offset:50176
	ds_read_b128 v[168:171], v246 offset:51200
	ds_read_b128 v[172:175], v246 offset:52224
	s_add_u32 s64, s64, 0x4000
	s_addc_u32 s65, s65, 0
	s_mov_b32 m0, s41
	ds_read_b128 v[176:179], v163 offset:32768
	ds_read_b128 v[180:183], v163 offset:33792
	ds_read_b128 v[184:187], v163 offset:34816
	ds_read_b128 v[188:191], v163 offset:35840
	ds_read_b128 v[192:195], v163 offset:36864
	ds_read_b128 v[196:199], v163 offset:37888
	ds_read_b128 v[200:203], v163 offset:38912
	ds_read_b128 v[204:207], v163 offset:39936
	global_load_lds_dwordx4 v150, s[64:65]
	s_mov_b32 m0, s42
	s_nop 0
	global_load_lds_dwordx4 v146, s[64:65]
	s_waitcnt vmcnt(8) lgkmcnt(0)
	s_barrier
	v_mfma_f32_16x16x32_bf16 v[124:127], v[128:131], v[176:179], v[124:127]
	v_mfma_f32_16x16x32_bf16 v[120:123], v[136:139], v[176:179], v[120:123]
	v_mfma_f32_16x16x32_bf16 v[108:111], v[128:131], v[184:187], v[108:111]
	v_mfma_f32_16x16x32_bf16 v[104:107], v[136:139], v[184:187], v[104:107]
	v_mfma_f32_16x16x32_bf16 v[92:95], v[128:131], v[192:195], v[92:95]
	v_mfma_f32_16x16x32_bf16 v[88:91], v[136:139], v[192:195], v[88:91]
	v_mfma_f32_16x16x32_bf16 v[76:79], v[128:131], v[200:203], v[76:79]
	v_mfma_f32_16x16x32_bf16 v[72:75], v[136:139], v[200:203], v[72:75]
	v_mfma_f32_16x16x32_bf16 v[124:127], v[132:135], v[180:183], v[124:127]
	v_mfma_f32_16x16x32_bf16 v[120:123], v[140:143], v[180:183], v[120:123]
	v_mfma_f32_16x16x32_bf16 v[108:111], v[132:135], v[188:191], v[108:111]
	v_mfma_f32_16x16x32_bf16 v[104:107], v[140:143], v[188:191], v[104:107]
	v_mfma_f32_16x16x32_bf16 v[92:95], v[132:135], v[196:199], v[92:95]
	v_mfma_f32_16x16x32_bf16 v[88:91], v[140:143], v[196:199], v[88:91]
	v_mfma_f32_16x16x32_bf16 v[76:79], v[132:135], v[204:207], v[76:79]
	v_mfma_f32_16x16x32_bf16 v[72:75], v[140:143], v[204:207], v[72:75]
	v_mfma_f32_16x16x32_bf16 v[116:119], v[156:159], v[176:179], v[116:119]
	v_mfma_f32_16x16x32_bf16 v[112:115], v[168:171], v[176:179], v[112:115]
	v_mfma_f32_16x16x32_bf16 v[100:103], v[156:159], v[184:187], v[100:103]
	v_mfma_f32_16x16x32_bf16 v[96:99], v[168:171], v[184:187], v[96:99]
	v_mfma_f32_16x16x32_bf16 v[84:87], v[156:159], v[192:195], v[84:87]
	v_mfma_f32_16x16x32_bf16 v[80:83], v[168:171], v[192:195], v[80:83]
	v_mfma_f32_16x16x32_bf16 v[68:71], v[156:159], v[200:203], v[68:71]
	v_mfma_f32_16x16x32_bf16 v[64:67], v[168:171], v[200:203], v[64:67]
	v_mfma_f32_16x16x32_bf16 v[116:119], v[164:167], v[180:183], v[116:119]
	v_mfma_f32_16x16x32_bf16 v[112:115], v[172:175], v[180:183], v[112:115]
	v_mfma_f32_16x16x32_bf16 v[100:103], v[164:167], v[188:191], v[100:103]
	v_mfma_f32_16x16x32_bf16 v[96:99], v[172:175], v[188:191], v[96:99]
	v_mfma_f32_16x16x32_bf16 v[84:87], v[164:167], v[196:199], v[84:87]
	v_mfma_f32_16x16x32_bf16 v[80:83], v[172:175], v[196:199], v[80:83]
	v_mfma_f32_16x16x32_bf16 v[68:71], v[164:167], v[204:207], v[68:71]
	v_mfma_f32_16x16x32_bf16 v[64:67], v[172:175], v[204:207], v[64:67]
	s_barrier
	s_add_u32 s64, s62, 0x8000
	s_addc_u32 s65, s63, 0
	s_add_i32 s69, s69, s30
	s_mov_b32 m0, s69
	ds_read_b128 v[176:179], v163 offset:49152
	ds_read_b128 v[180:183], v163 offset:50176
	ds_read_b128 v[184:187], v163 offset:51200
	ds_read_b128 v[188:191], v163 offset:52224
	ds_read_b128 v[192:195], v163 offset:53248
	ds_read_b128 v[196:199], v163 offset:54272
	ds_read_b128 v[200:203], v163 offset:55296
	ds_read_b128 v[204:207], v163 offset:56320
	global_load_lds_dwordx4 v148, s[64:65]
	s_add_i32 m0, s69, 0x2000
	s_add_u32 s62, s62, 0xc000
	s_addc_u32 s63, s63, 0
	s_add_i32 s91, s70, s30
	global_load_lds_dwordx4 v144, s[64:65]
	s_mov_b32 m0, s91
	s_nop 0
	global_load_lds_dwordx4 v148, s[62:63]
	s_add_i32 m0, s91, 0x2000
	s_nop 0
	global_load_lds_dwordx4 v144, s[62:63]
	s_mov_b32 m0, s54
	s_nop 0
	global_load_lds_dwordx4 v150, s[20:21]
	s_mov_b32 m0, s55
	s_nop 0
	global_load_lds_dwordx4 v146, s[20:21]
	s_waitcnt vmcnt(8) lgkmcnt(0)
	s_barrier
	v_mfma_f32_16x16x32_bf16 v[60:63], v[128:131], v[176:179], v[60:63]
	v_mfma_f32_16x16x32_bf16 v[56:59], v[136:139], v[176:179], v[56:59]
	v_mfma_f32_16x16x32_bf16 v[44:47], v[128:131], v[184:187], v[44:47]
	v_mfma_f32_16x16x32_bf16 v[40:43], v[136:139], v[184:187], v[40:43]
	v_mfma_f32_16x16x32_bf16 v[28:31], v[128:131], v[192:195], v[28:31]
	v_mfma_f32_16x16x32_bf16 v[24:27], v[136:139], v[192:195], v[24:27]
	v_mfma_f32_16x16x32_bf16 v[12:15], v[128:131], v[200:203], v[12:15]
	v_mfma_f32_16x16x32_bf16 v[8:11], v[136:139], v[200:203], v[8:11]
	v_mfma_f32_16x16x32_bf16 v[60:63], v[132:135], v[180:183], v[60:63]
	v_mfma_f32_16x16x32_bf16 v[56:59], v[140:143], v[180:183], v[56:59]
	v_mfma_f32_16x16x32_bf16 v[44:47], v[132:135], v[188:191], v[44:47]
	v_mfma_f32_16x16x32_bf16 v[40:43], v[140:143], v[188:191], v[40:43]
	v_mfma_f32_16x16x32_bf16 v[28:31], v[132:135], v[196:199], v[28:31]
	v_mfma_f32_16x16x32_bf16 v[24:27], v[140:143], v[196:199], v[24:27]
	v_mfma_f32_16x16x32_bf16 v[12:15], v[132:135], v[204:207], v[12:15]
	v_mfma_f32_16x16x32_bf16 v[8:11], v[140:143], v[204:207], v[8:11]
	v_mfma_f32_16x16x32_bf16 v[52:55], v[156:159], v[176:179], v[52:55]
	v_mfma_f32_16x16x32_bf16 v[48:51], v[168:171], v[176:179], v[48:51]
	v_mfma_f32_16x16x32_bf16 v[36:39], v[156:159], v[184:187], v[36:39]
	v_mfma_f32_16x16x32_bf16 v[32:35], v[168:171], v[184:187], v[32:35]
	v_mfma_f32_16x16x32_bf16 v[20:23], v[156:159], v[192:195], v[20:23]
	v_mfma_f32_16x16x32_bf16 v[16:19], v[168:171], v[192:195], v[16:19]
	v_mfma_f32_16x16x32_bf16 v[4:7], v[156:159], v[200:203], v[4:7]
	v_mfma_f32_16x16x32_bf16 v[0:3], v[168:171], v[200:203], v[0:3]
	v_mfma_f32_16x16x32_bf16 v[52:55], v[164:167], v[180:183], v[52:55]
	v_mfma_f32_16x16x32_bf16 v[48:51], v[172:175], v[180:183], v[48:51]
	v_mfma_f32_16x16x32_bf16 v[36:39], v[164:167], v[188:191], v[36:39]
	v_mfma_f32_16x16x32_bf16 v[32:35], v[172:175], v[188:191], v[32:35]
	v_mfma_f32_16x16x32_bf16 v[20:23], v[164:167], v[196:199], v[20:23]
	v_mfma_f32_16x16x32_bf16 v[16:19], v[172:175], v[196:199], v[16:19]
	v_mfma_f32_16x16x32_bf16 v[4:7], v[164:167], v[204:207], v[4:7]
	v_mfma_f32_16x16x32_bf16 v[0:3], v[172:175], v[204:207], v[0:3]
	s_barrier
	s_add_i32 s68, s68, 2
	s_add_u32 s18, s18, 0x10000
	s_addc_u32 s19, s19, 0
	s_add_u32 s66, s66, 0x10000
	s_addc_u32 s67, s67, 0
	s_cmp_gt_u32 s68, 13
	s_cbranch_scc0 .LBB0_1356
	s_and_b64 vcc, exec, s[6:7]
	s_cbranch_vccz .LBB0_1359
	s_barrier
